# GEMM K-loops: removed the back-to-back setprio 0/1 flips and the lgkmcnt waits made redundant by the explicit drain before each barrier; gMLP pairing guarded to 256-workgroup grids
# speedup vs baseline: 1.0002x; 1.0002x over previous
; #define PG8_LDA(dst, b, h) do { _Pragma("unroll") for (int m = 0; m < 4; ++m) _Pragma("unroll") for (int k = 0; k < 2; ++k) dst[m][k] = *(const LAS bf16x8*)(lds + PG8_SA(b, h) + aoff + m * 2048 + k * 1024); } while (0)
; #define PG8_LDB(dst, b, h) do { _Pragma("unroll") for (int n = 0; n < 2; ++n) _Pragma("unroll") for (int k = 0; k < 2; ++k) dst[n][k] = *(const LAS bf16x8*)(lds + PG8_SB(b, h) + boff + n * 2048 + k * 1024); } while (0)
; #define PG8_MMA(ai, bj, At, Bt) do { __builtin_amdgcn_s_setprio(1); _Pragma("unroll") for (int m = 0; m < 4; ++m) _Pragma("unroll") for (int n = 0; n < 2; ++n) _Pragma("unroll") for (int k = 0; k < 2; ++k) \
;         acc[ai][bj][m][n] = __builtin_amdgcn_mfma_f32_16x16x32_bf16(Bt[n][k], At[m][k], acc[ai][bj][m][n], 0, 0, 0); __builtin_amdgcn_s_setprio(0); } while (0)
; #define PG8_WAIT_V(n) asm volatile("s_waitcnt vmcnt(" #n ")" ::: "memory")
; #define PG8_WAIT_L(n) asm volatile("s_waitcnt lgkmcnt(" #n ")" ::: "memory")
; #define PG8_BAR __builtin_amdgcn_s_barrier()
; #define PG8_SCHED __builtin_amdgcn_sched_barrier(0)
; template <class Epi, class Sched>
; __device__ __forceinline__ void gemm_phase(LAS unsigned char* lds, const Gemm g, const Sched& S, const Epi& E) {
;     ...
;             PG8_LDB(B0, 0, 0); PG8_LDB(B1, 0, 1); PG8_SCHED; PG8_LDA(At, 0, 0); PG8_STAGE(PG8_SA(1, 1), a1 + hstepA, voffA);
;             PG8_WAIT_V(8); PG8_WAIT_L(0); PG8_BAR; PG8_MMA(0, 0, At, B0); PG8_MMA(0, 1, At, B1); PG8_BAR; PG8_SCHED;
;             PG8_LDA(At, 0, 1); PG8_STAGE(PG8_SB(0, 0), b2, voffB); PG8_STAGE(PG8_SB(0, 1), b2 + hstepB, voffB); PG8_STAGE(PG8_SA(0, 0), a2, voffA);
;             PG8_WAIT_V(8); PG8_WAIT_L(0); PG8_BAR; PG8_MMA(1, 0, At, B0); PG8_MMA(1, 1, At, B1); PG8_BAR; PG8_SCHED;
.LBB0_95:
	ds_read_b128 v[174:177], v155
	ds_read_b128 v[178:181], v155 offset:1024
	ds_read_b128 v[182:185], v155 offset:2048
	ds_read_b128 v[186:189], v155 offset:3072
	ds_read_b128 v[190:193], v156
	ds_read_b128 v[194:197], v156 offset:1024
	ds_read_b128 v[202:205], v156 offset:2048
	ds_read_b128 v[206:209], v156 offset:3072
	s_add_u32 s26, s24, 0x100
	s_addc_u32 s27, s25, 0
	s_cmp_eq_u32 s62, 12
	s_cselect_b32 s34, s19, s26
	s_cselect_b32 s35, s11, s27
	s_cselect_b32 s30, s56, s57
	s_cselect_b32 s31, s13, s61
	s_add_u32 s28, s34, 0x80
	s_addc_u32 s29, s35, 0
	ds_read_b128 v[210:213], v157
	ds_read_b128 v[214:217], v157 offset:1024
	ds_read_b128 v[218:221], v157 offset:2048
	ds_read_b128 v[222:225], v157 offset:3072
	ds_read_b128 v[226:229], v157 offset:4096
	ds_read_b128 v[230:233], v157 offset:5120
	ds_read_b128 v[234:237], v157 offset:6144
	ds_read_b128 v[238:241], v157 offset:7168
	s_add_u32 s24, s24, 0x20080
	v_readfirstlane_b32 s63, v158
	s_addc_u32 s25, s25, 0
	s_mov_b32 m0, s63
	s_nop 0
	global_load_lds_dwordx4 v131, s[24:25]
	v_readfirstlane_b32 s63, v159
	s_add_i32 s63, s63, 0
	s_add_i32 s63, s63, 0xe000
	s_mov_b32 m0, s63
	s_nop 0
	global_load_lds_dwordx4 v145, s[24:25]
	s_waitcnt vmcnt(8)
	s_waitcnt lgkmcnt(0)
	s_barrier
	s_setprio 1
	v_mfma_f32_16x16x32_bf16 v[126:129], v[174:177], v[210:213], v[126:129]
	v_mfma_f32_16x16x32_bf16 v[122:125], v[182:185], v[210:213], v[122:125]
	v_mfma_f32_16x16x32_bf16 v[110:113], v[174:177], v[218:221], v[110:113]
	v_mfma_f32_16x16x32_bf16 v[106:109], v[182:185], v[218:221], v[106:109]
	v_mfma_f32_16x16x32_bf16 v[94:97], v[174:177], v[226:229], v[94:97]
	v_mfma_f32_16x16x32_bf16 v[90:93], v[182:185], v[226:229], v[90:93]
	v_mfma_f32_16x16x32_bf16 v[78:81], v[174:177], v[234:237], v[78:81]
	v_mfma_f32_16x16x32_bf16 v[74:77], v[182:185], v[234:237], v[74:77]
	v_mfma_f32_16x16x32_bf16 v[126:129], v[178:181], v[214:217], v[126:129]
	v_mfma_f32_16x16x32_bf16 v[122:125], v[186:189], v[214:217], v[122:125]
	v_mfma_f32_16x16x32_bf16 v[110:113], v[178:181], v[222:225], v[110:113]
	v_mfma_f32_16x16x32_bf16 v[106:109], v[186:189], v[222:225], v[106:109]
	v_mfma_f32_16x16x32_bf16 v[94:97], v[178:181], v[230:233], v[94:97]
	v_mfma_f32_16x16x32_bf16 v[90:93], v[186:189], v[230:233], v[90:93]
	v_mfma_f32_16x16x32_bf16 v[78:81], v[178:181], v[238:241], v[78:81]
	v_mfma_f32_16x16x32_bf16 v[74:77], v[186:189], v[238:241], v[74:77]
	v_mfma_f32_16x16x32_bf16 v[118:121], v[190:193], v[210:213], v[118:121]
	v_mfma_f32_16x16x32_bf16 v[114:117], v[202:205], v[210:213], v[114:117]
	v_mfma_f32_16x16x32_bf16 v[102:105], v[190:193], v[218:221], v[102:105]
	v_mfma_f32_16x16x32_bf16 v[98:101], v[202:205], v[218:221], v[98:101]
	v_mfma_f32_16x16x32_bf16 v[86:89], v[190:193], v[226:229], v[86:89]
	v_mfma_f32_16x16x32_bf16 v[82:85], v[202:205], v[226:229], v[82:85]
	v_mfma_f32_16x16x32_bf16 v[70:73], v[190:193], v[234:237], v[70:73]
	v_mfma_f32_16x16x32_bf16 v[66:69], v[202:205], v[234:237], v[66:69]
	v_mfma_f32_16x16x32_bf16 v[118:121], v[194:197], v[214:217], v[118:121]
	v_mfma_f32_16x16x32_bf16 v[114:117], v[206:209], v[214:217], v[114:117]
	v_mfma_f32_16x16x32_bf16 v[102:105], v[194:197], v[222:225], v[102:105]
	v_mfma_f32_16x16x32_bf16 v[98:101], v[206:209], v[222:225], v[98:101]
	v_mfma_f32_16x16x32_bf16 v[86:89], v[194:197], v[230:233], v[86:89]
	v_mfma_f32_16x16x32_bf16 v[82:85], v[206:209], v[230:233], v[82:85]
	v_mfma_f32_16x16x32_bf16 v[70:73], v[194:197], v[238:241], v[70:73]
	v_mfma_f32_16x16x32_bf16 v[66:69], v[206:209], v[238:241], v[66:69]
	s_setprio 0
	s_barrier
	ds_read_b128 v[210:213], v157 offset:16384
	ds_read_b128 v[214:217], v157 offset:17408
	ds_read_b128 v[218:221], v157 offset:18432
	ds_read_b128 v[222:225], v157 offset:19456
	ds_read_b128 v[226:229], v157 offset:20480
	ds_read_b128 v[230:233], v157 offset:21504
	ds_read_b128 v[234:237], v157 offset:22528
	ds_read_b128 v[238:241], v157 offset:23552
	v_readfirstlane_b32 s24, v160
	s_mov_b32 m0, s24
	s_nop 0
	global_load_lds_dwordx4 v144, s[30:31]
	v_readfirstlane_b32 s24, v161
	s_mov_b32 m0, s24
	s_nop 0
	global_load_lds_dwordx4 v146, s[30:31]
	s_add_u32 s24, s30, 0x10000
	s_addc_u32 s25, s31, 0
	v_readfirstlane_b32 s63, v162
	s_mov_b32 m0, s63
	s_nop 0
	global_load_lds_dwordx4 v144, s[24:25]
	v_readfirstlane_b32 s63, v163
	s_mov_b32 m0, s63
	s_nop 0
	global_load_lds_dwordx4 v146, s[24:25]
	v_readfirstlane_b32 s24, v164
	s_mov_b32 m0, s24
	s_nop 0
	global_load_lds_dwordx4 v131, s[34:35]
	v_readfirstlane_b32 s24, v165
	s_mov_b32 m0, s24
	s_nop 0
	global_load_lds_dwordx4 v145, s[34:35]
	s_waitcnt vmcnt(8)
	s_waitcnt lgkmcnt(0)
	s_barrier
; #define PG8_LDA(dst, b, h) do { _Pragma("unroll") for (int m = 0; m < 4; ++m) _Pragma("unroll") for (int k = 0; k < 2; ++k) dst[m][k] = *(const LAS bf16x8*)(lds + PG8_SA(b, h) + aoff + m * 2048 + k * 1024); } while (0)
; #define PG8_LDB(dst, b, h) do { _Pragma("unroll") for (int n = 0; n < 2; ++n) _Pragma("unroll") for (int k = 0; k < 2; ++k) dst[n][k] = *(const LAS bf16x8*)(lds + PG8_SB(b, h) + boff + n * 2048 + k * 1024); } while (0)
; #define PG8_MMA(ai, bj, At, Bt) do { __builtin_amdgcn_s_setprio(1); _Pragma("unroll") for (int m = 0; m < 4; ++m) _Pragma("unroll") for (int n = 0; n < 2; ++n) _Pragma("unroll") for (int k = 0; k < 2; ++k) \
;         acc[ai][bj][m][n] = __builtin_amdgcn_mfma_f32_16x16x32_bf16(Bt[n][k], At[m][k], acc[ai][bj][m][n], 0, 0, 0); __builtin_amdgcn_s_setprio(0); } while (0)
; #define PG8_WAIT_V(n) asm volatile("s_waitcnt vmcnt(" #n ")" ::: "memory")
; #define PG8_WAIT_L(n) asm volatile("s_waitcnt lgkmcnt(" #n ")" ::: "memory")
; #define PG8_BAR __builtin_amdgcn_s_barrier()
; #define PG8_SCHED __builtin_amdgcn_sched_barrier(0)
; template <class Epi, class Sched>
; __device__ __forceinline__ void gemm_phase(LAS unsigned char* lds, const Gemm g, const Sched& S, const Epi& E) {
;     ...
;             PG8_WAIT_V(8); PG8_WAIT_L(0); PG8_BAR; PG8_MMA(1, 0, At, B0); PG8_MMA(1, 1, At, B1); PG8_BAR; PG8_SCHED;
;             PG8_LDB(B0, 1, 0); PG8_LDB(B1, 1, 1); PG8_SCHED; PG8_LDA(At, 1, 0); PG8_STAGE(PG8_SA(0, 1), a2 + hstepA, voffA);
;             PG8_WAIT_V(8); PG8_WAIT_L(0); PG8_BAR; PG8_MMA(0, 0, At, B0); PG8_MMA(0, 1, At, B1); PG8_BAR; PG8_SCHED;
	s_setprio 1
	v_mfma_f32_16x16x32_bf16 v[62:65], v[174:177], v[210:213], v[62:65]
	v_mfma_f32_16x16x32_bf16 v[58:61], v[182:185], v[210:213], v[58:61]
	v_mfma_f32_16x16x32_bf16 v[46:49], v[174:177], v[218:221], v[46:49]
	v_mfma_f32_16x16x32_bf16 v[42:45], v[182:185], v[218:221], v[42:45]
	v_mfma_f32_16x16x32_bf16 v[30:33], v[174:177], v[226:229], v[30:33]
	v_mfma_f32_16x16x32_bf16 v[26:29], v[182:185], v[226:229], v[26:29]
	v_mfma_f32_16x16x32_bf16 v[14:17], v[174:177], v[234:237], v[14:17]
	v_mfma_f32_16x16x32_bf16 v[10:13], v[182:185], v[234:237], v[10:13]
	v_mfma_f32_16x16x32_bf16 v[62:65], v[178:181], v[214:217], v[62:65]
	v_mfma_f32_16x16x32_bf16 v[58:61], v[186:189], v[214:217], v[58:61]
	v_mfma_f32_16x16x32_bf16 v[46:49], v[178:181], v[222:225], v[46:49]
	v_mfma_f32_16x16x32_bf16 v[42:45], v[186:189], v[222:225], v[42:45]
	v_mfma_f32_16x16x32_bf16 v[30:33], v[178:181], v[230:233], v[30:33]
	v_mfma_f32_16x16x32_bf16 v[26:29], v[186:189], v[230:233], v[26:29]
	v_mfma_f32_16x16x32_bf16 v[14:17], v[178:181], v[238:241], v[14:17]
	v_mfma_f32_16x16x32_bf16 v[10:13], v[186:189], v[238:241], v[10:13]
	v_mfma_f32_16x16x32_bf16 v[54:57], v[190:193], v[210:213], v[54:57]
	v_mfma_f32_16x16x32_bf16 v[50:53], v[202:205], v[210:213], v[50:53]
	v_mfma_f32_16x16x32_bf16 v[38:41], v[190:193], v[218:221], v[38:41]
	v_mfma_f32_16x16x32_bf16 v[34:37], v[202:205], v[218:221], v[34:37]
	v_mfma_f32_16x16x32_bf16 v[22:25], v[190:193], v[226:229], v[22:25]
	v_mfma_f32_16x16x32_bf16 v[18:21], v[202:205], v[226:229], v[18:21]
	v_mfma_f32_16x16x32_bf16 v[6:9], v[190:193], v[234:237], v[6:9]
	v_mfma_f32_16x16x32_bf16 v[2:5], v[202:205], v[234:237], v[2:5]
	v_mfma_f32_16x16x32_bf16 v[54:57], v[194:197], v[214:217], v[54:57]
	v_mfma_f32_16x16x32_bf16 v[50:53], v[206:209], v[214:217], v[50:53]
	v_mfma_f32_16x16x32_bf16 v[38:41], v[194:197], v[222:225], v[38:41]
	v_mfma_f32_16x16x32_bf16 v[34:37], v[206:209], v[222:225], v[34:37]
	v_mfma_f32_16x16x32_bf16 v[22:25], v[194:197], v[230:233], v[22:25]
	v_mfma_f32_16x16x32_bf16 v[18:21], v[206:209], v[230:233], v[18:21]
	v_mfma_f32_16x16x32_bf16 v[6:9], v[194:197], v[238:241], v[6:9]
	v_mfma_f32_16x16x32_bf16 v[2:5], v[206:209], v[238:241], v[2:5]
	s_setprio 0
	s_barrier
	ds_read_b128 v[174:177], v166
	ds_read_b128 v[178:181], v166 offset:1024
	ds_read_b128 v[182:185], v166 offset:2048
	ds_read_b128 v[186:189], v166 offset:3072
	ds_read_b128 v[190:193], v167
	ds_read_b128 v[194:197], v167 offset:1024
	ds_read_b128 v[202:205], v167 offset:2048
	ds_read_b128 v[206:209], v167 offset:3072
	ds_read_b128 v[210:213], v157 offset:32768
	ds_read_b128 v[214:217], v157 offset:33792
	ds_read_b128 v[218:221], v157 offset:34816
	ds_read_b128 v[222:225], v157 offset:35840
	ds_read_b128 v[226:229], v157 offset:36864
	ds_read_b128 v[230:233], v157 offset:37888
	ds_read_b128 v[234:237], v157 offset:38912
	ds_read_b128 v[238:241], v157 offset:39936
	s_add_u32 s24, s34, 0x20000
	s_addc_u32 s25, s35, 0
	v_readfirstlane_b32 s34, v168
	s_mov_b32 m0, s34
	s_nop 0
	global_load_lds_dwordx4 v131, s[24:25]
	v_readfirstlane_b32 s34, v169
	s_mov_b32 m0, s34
	s_nop 0
	global_load_lds_dwordx4 v145, s[24:25]
	s_waitcnt vmcnt(8)
	s_waitcnt lgkmcnt(0)
	s_barrier
	s_setprio 1
	v_mfma_f32_16x16x32_bf16 v[126:129], v[174:177], v[210:213], v[126:129]
	v_mfma_f32_16x16x32_bf16 v[122:125], v[182:185], v[210:213], v[122:125]
	v_mfma_f32_16x16x32_bf16 v[110:113], v[174:177], v[218:221], v[110:113]
	v_mfma_f32_16x16x32_bf16 v[106:109], v[182:185], v[218:221], v[106:109]
	v_mfma_f32_16x16x32_bf16 v[94:97], v[174:177], v[226:229], v[94:97]
	v_mfma_f32_16x16x32_bf16 v[90:93], v[182:185], v[226:229], v[90:93]
	v_mfma_f32_16x16x32_bf16 v[78:81], v[174:177], v[234:237], v[78:81]
	v_mfma_f32_16x16x32_bf16 v[74:77], v[182:185], v[234:237], v[74:77]
	v_mfma_f32_16x16x32_bf16 v[126:129], v[178:181], v[214:217], v[126:129]
	v_mfma_f32_16x16x32_bf16 v[122:125], v[186:189], v[214:217], v[122:125]
	v_mfma_f32_16x16x32_bf16 v[110:113], v[178:181], v[222:225], v[110:113]
	v_mfma_f32_16x16x32_bf16 v[106:109], v[186:189], v[222:225], v[106:109]
	v_mfma_f32_16x16x32_bf16 v[94:97], v[178:181], v[230:233], v[94:97]
	v_mfma_f32_16x16x32_bf16 v[90:93], v[186:189], v[230:233], v[90:93]
	v_mfma_f32_16x16x32_bf16 v[78:81], v[178:181], v[238:241], v[78:81]
	v_mfma_f32_16x16x32_bf16 v[74:77], v[186:189], v[238:241], v[74:77]
	v_mfma_f32_16x16x32_bf16 v[118:121], v[190:193], v[210:213], v[118:121]
	v_mfma_f32_16x16x32_bf16 v[114:117], v[202:205], v[210:213], v[114:117]
	v_mfma_f32_16x16x32_bf16 v[102:105], v[190:193], v[218:221], v[102:105]
	v_mfma_f32_16x16x32_bf16 v[98:101], v[202:205], v[218:221], v[98:101]
	v_mfma_f32_16x16x32_bf16 v[86:89], v[190:193], v[226:229], v[86:89]
	v_mfma_f32_16x16x32_bf16 v[82:85], v[202:205], v[226:229], v[82:85]
	v_mfma_f32_16x16x32_bf16 v[70:73], v[190:193], v[234:237], v[70:73]
	v_mfma_f32_16x16x32_bf16 v[66:69], v[202:205], v[234:237], v[66:69]
	v_mfma_f32_16x16x32_bf16 v[118:121], v[194:197], v[214:217], v[118:121]
	v_mfma_f32_16x16x32_bf16 v[114:117], v[206:209], v[214:217], v[114:117]
	v_mfma_f32_16x16x32_bf16 v[102:105], v[194:197], v[222:225], v[102:105]
	v_mfma_f32_16x16x32_bf16 v[98:101], v[206:209], v[222:225], v[98:101]
	v_mfma_f32_16x16x32_bf16 v[86:89], v[194:197], v[230:233], v[86:89]
	v_mfma_f32_16x16x32_bf16 v[82:85], v[206:209], v[230:233], v[82:85]
	v_mfma_f32_16x16x32_bf16 v[70:73], v[194:197], v[238:241], v[70:73]
	v_mfma_f32_16x16x32_bf16 v[66:69], v[206:209], v[238:241], v[66:69]
	s_setprio 0
	s_barrier
; #define PG8_LDA(dst, b, h) do { _Pragma("unroll") for (int m = 0; m < 4; ++m) _Pragma("unroll") for (int k = 0; k < 2; ++k) dst[m][k] = *(const LAS bf16x8*)(lds + PG8_SA(b, h) + aoff + m * 2048 + k * 1024); } while (0)
; #define PG8_MMA(ai, bj, At, Bt) do { __builtin_amdgcn_s_setprio(1); _Pragma("unroll") for (int m = 0; m < 4; ++m) _Pragma("unroll") for (int n = 0; n < 2; ++n) _Pragma("unroll") for (int k = 0; k < 2; ++k) \
;         acc[ai][bj][m][n] = __builtin_amdgcn_mfma_f32_16x16x32_bf16(Bt[n][k], At[m][k], acc[ai][bj][m][n], 0, 0, 0); __builtin_amdgcn_s_setprio(0); } while (0)
; #define PG8_WAIT_V(n) asm volatile("s_waitcnt vmcnt(" #n ")" ::: "memory")
; #define PG8_WAIT_L(n) asm volatile("s_waitcnt lgkmcnt(" #n ")" ::: "memory")
; #define PG8_BAR __builtin_amdgcn_s_barrier()
; #define PG8_SCHED __builtin_amdgcn_sched_barrier(0)
; template <class Epi, class Sched>
; __device__ __forceinline__ void gemm_phase(LAS unsigned char* lds, const Gemm g, const Sched& S, const Epi& E) {
;     ...
;             PG8_LDA(At, 1, 1); PG8_STAGE(PG8_SB(1, 0), b3, voffB); PG8_STAGE(PG8_SB(1, 1), b3 + hstepB, voffB); PG8_STAGE(PG8_SA(1, 0), a3, voffA);
;             PG8_WAIT_V(8); PG8_WAIT_L(0); PG8_BAR; PG8_MMA(1, 0, At, B0); PG8_MMA(1, 1, At, B1); PG8_BAR; PG8_SCHED;
;         }
;         if (wr == 0) PG8_BAR;
	ds_read_b128 v[210:213], v157 offset:49152
	ds_read_b128 v[214:217], v157 offset:50176
	ds_read_b128 v[218:221], v157 offset:51200
	ds_read_b128 v[222:225], v157 offset:52224
	ds_read_b128 v[226:229], v157 offset:53248
	ds_read_b128 v[230:233], v157 offset:54272
	ds_read_b128 v[234:237], v157 offset:55296
	ds_read_b128 v[238:241], v157 offset:56320
	s_add_u32 s24, s30, 0x80
	s_addc_u32 s25, s31, 0
	v_readfirstlane_b32 s34, v147
	s_mov_b32 m0, s34
	s_nop 0
	global_load_lds_dwordx4 v144, s[24:25]
	v_readfirstlane_b32 s34, v148
	s_mov_b32 m0, s34
	s_nop 0
	global_load_lds_dwordx4 v146, s[24:25]
	s_add_u32 s24, s30, 0x10080
	s_addc_u32 s25, s31, 0
	v_readfirstlane_b32 s30, v151
	s_mov_b32 m0, s30
	s_nop 0
	global_load_lds_dwordx4 v144, s[24:25]
	v_readfirstlane_b32 s30, v152
	s_mov_b32 m0, s30
	s_nop 0
	global_load_lds_dwordx4 v146, s[24:25]
	v_readfirstlane_b32 s24, v149
	s_mov_b32 m0, s24
	s_nop 0
	global_load_lds_dwordx4 v131, s[28:29]
	v_readfirstlane_b32 s24, v150
	s_mov_b32 m0, s24
	s_nop 0
	global_load_lds_dwordx4 v145, s[28:29]
	s_waitcnt vmcnt(8)
	s_waitcnt lgkmcnt(0)
	s_barrier
	s_setprio 1
	v_mfma_f32_16x16x32_bf16 v[62:65], v[174:177], v[210:213], v[62:65]
	v_mfma_f32_16x16x32_bf16 v[58:61], v[182:185], v[210:213], v[58:61]
	v_mfma_f32_16x16x32_bf16 v[46:49], v[174:177], v[218:221], v[46:49]
	v_mfma_f32_16x16x32_bf16 v[42:45], v[182:185], v[218:221], v[42:45]
	v_mfma_f32_16x16x32_bf16 v[30:33], v[174:177], v[226:229], v[30:33]
	v_mfma_f32_16x16x32_bf16 v[26:29], v[182:185], v[226:229], v[26:29]
	v_mfma_f32_16x16x32_bf16 v[14:17], v[174:177], v[234:237], v[14:17]
	v_mfma_f32_16x16x32_bf16 v[10:13], v[182:185], v[234:237], v[10:13]
	v_mfma_f32_16x16x32_bf16 v[62:65], v[178:181], v[214:217], v[62:65]
	v_mfma_f32_16x16x32_bf16 v[58:61], v[186:189], v[214:217], v[58:61]
	v_mfma_f32_16x16x32_bf16 v[46:49], v[178:181], v[222:225], v[46:49]
	v_mfma_f32_16x16x32_bf16 v[42:45], v[186:189], v[222:225], v[42:45]
	v_mfma_f32_16x16x32_bf16 v[30:33], v[178:181], v[230:233], v[30:33]
	v_mfma_f32_16x16x32_bf16 v[26:29], v[186:189], v[230:233], v[26:29]
	v_mfma_f32_16x16x32_bf16 v[14:17], v[178:181], v[238:241], v[14:17]
	v_mfma_f32_16x16x32_bf16 v[10:13], v[186:189], v[238:241], v[10:13]
	v_mfma_f32_16x16x32_bf16 v[54:57], v[190:193], v[210:213], v[54:57]
	v_mfma_f32_16x16x32_bf16 v[50:53], v[202:205], v[210:213], v[50:53]
	v_mfma_f32_16x16x32_bf16 v[38:41], v[190:193], v[218:221], v[38:41]
	v_mfma_f32_16x16x32_bf16 v[34:37], v[202:205], v[218:221], v[34:37]
	v_mfma_f32_16x16x32_bf16 v[22:25], v[190:193], v[226:229], v[22:25]
	v_mfma_f32_16x16x32_bf16 v[18:21], v[202:205], v[226:229], v[18:21]
	v_mfma_f32_16x16x32_bf16 v[6:9], v[190:193], v[234:237], v[6:9]
	v_mfma_f32_16x16x32_bf16 v[2:5], v[202:205], v[234:237], v[2:5]
	v_mfma_f32_16x16x32_bf16 v[54:57], v[194:197], v[214:217], v[54:57]
	v_mfma_f32_16x16x32_bf16 v[50:53], v[206:209], v[214:217], v[50:53]
	v_mfma_f32_16x16x32_bf16 v[38:41], v[194:197], v[222:225], v[38:41]
	v_mfma_f32_16x16x32_bf16 v[34:37], v[206:209], v[222:225], v[34:37]
	v_mfma_f32_16x16x32_bf16 v[22:25], v[194:197], v[230:233], v[22:25]
	v_mfma_f32_16x16x32_bf16 v[18:21], v[206:209], v[230:233], v[18:21]
	v_mfma_f32_16x16x32_bf16 v[6:9], v[194:197], v[238:241], v[6:9]
	v_mfma_f32_16x16x32_bf16 v[2:5], v[206:209], v[238:241], v[2:5]
	s_setprio 0
	s_barrier
	s_add_i32 s62, s62, 2
	s_add_u32 s57, s57, 0x100
	s_addc_u32 s61, s61, 0
	s_cmp_gt_u32 s62, 13
	s_mov_b64 s[24:25], s[26:27]
	s_cbranch_scc0 .LBB0_95
	s_and_b64 vcc, exec, s[8:9]
	s_cbranch_vccz .LBB0_98
	s_barrier

; #define PG8_LDA(dst, b, h) do { _Pragma("unroll") for (int m = 0; m < 4; ++m) _Pragma("unroll") for (int k = 0; k < 2; ++k) dst[m][k] = *(const LAS bf16x8*)(lds + PG8_SA(b, h) + aoff + m * 2048 + k * 1024); } while (0)
; #define PG8_LDB(dst, b, h) do { _Pragma("unroll") for (int n = 0; n < 2; ++n) _Pragma("unroll") for (int k = 0; k < 2; ++k) dst[n][k] = *(const LAS bf16x8*)(lds + PG8_SB(b, h) + boff + n * 2048 + k * 1024); } while (0)
; #define PG8_MMA(ai, bj, At, Bt) do { __builtin_amdgcn_s_setprio(1); _Pragma("unroll") for (int m = 0; m < 4; ++m) _Pragma("unroll") for (int n = 0; n < 2; ++n) _Pragma("unroll") for (int k = 0; k < 2; ++k) \
;         acc[ai][bj][m][n] = __builtin_amdgcn_mfma_f32_16x16x32_bf16(Bt[n][k], At[m][k], acc[ai][bj][m][n], 0, 0, 0); __builtin_amdgcn_s_setprio(0); } while (0)
; #define PG8_WAIT_V(n) asm volatile("s_waitcnt vmcnt(" #n ")" ::: "memory")
; #define PG8_WAIT_L(n) asm volatile("s_waitcnt lgkmcnt(" #n ")" ::: "memory")
; #define PG8_BAR __builtin_amdgcn_s_barrier()
; #define PG8_SCHED __builtin_amdgcn_sched_barrier(0)
; template <class Epi, class Sched>
; __device__ __forceinline__ void gemm_phase(LAS unsigned char* lds, const Gemm g, const Sched& S, const Epi& E) {
;     ...
;             PG8_LDB(B0, 0, 0); PG8_LDB(B1, 0, 1); PG8_SCHED; PG8_LDA(At, 0, 0); PG8_STAGE(PG8_SA(1, 1), a1 + hstepA, voffA);
;             PG8_WAIT_V(8); PG8_WAIT_L(0); PG8_BAR; PG8_MMA(0, 0, At, B0); PG8_MMA(0, 1, At, B1); PG8_BAR; PG8_SCHED;
;             PG8_LDA(At, 0, 1); PG8_STAGE(PG8_SB(0, 0), b2, voffB); PG8_STAGE(PG8_SB(0, 1), b2 + hstepB, voffB); PG8_STAGE(PG8_SA(0, 0), a2, voffA);
;             PG8_WAIT_V(8); PG8_WAIT_L(0); PG8_BAR; PG8_MMA(1, 0, At, B0); PG8_MMA(1, 1, At, B1); PG8_BAR; PG8_SCHED;
.LBB0_618:
	v_add_u32_e32 v3, 0x10000, v183
	ds_read_b128 v[134:137], v3
	ds_read_b128 v[138:141], v3 offset:1024
	ds_read_b128 v[142:145], v3 offset:2048
	ds_read_b128 v[146:149], v3 offset:3072
	v_add_u32_e32 v3, 0x14000, v183
	ds_read_b128 v[150:153], v3
	ds_read_b128 v[154:157], v3 offset:1024
	ds_read_b128 v[186:189], v3 offset:2048
	ds_read_b128 v[190:193], v3 offset:3072
	s_add_u32 s26, s24, 0x100
	s_addc_u32 s27, s25, 0
	s_cmp_eq_u32 s66, 12
	s_cselect_b32 s44, s62, s26
	s_cselect_b32 s45, s13, s27
	s_cselect_b32 s30, s63, s64
	s_cselect_b32 s31, s15, s65
	s_add_u32 s28, s44, 0x80
	s_addc_u32 s29, s45, 0
	ds_read_b128 v[194:197], v184
	ds_read_b128 v[198:201], v184 offset:1024
	ds_read_b128 v[202:205], v184 offset:2048
	ds_read_b128 v[206:209], v184 offset:3072
	ds_read_b128 v[210:213], v184 offset:4096
	ds_read_b128 v[214:217], v184 offset:5120
	ds_read_b128 v[218:221], v184 offset:6144
	ds_read_b128 v[222:225], v184 offset:7168
	s_add_u32 s24, s24, 0x20080
	s_addc_u32 s25, s25, 0
	s_mov_b32 m0, s59
	s_nop 0
	global_load_lds_dwordx4 v1, s[24:25]
	s_add_i32 s36, s20, 0xe000
	s_mov_b32 m0, s36
	s_nop 0
	global_load_lds_dwordx4 v180, s[24:25]
	s_waitcnt vmcnt(8)
	s_waitcnt lgkmcnt(0)
	s_barrier
	s_setprio 1
	v_mfma_f32_16x16x32_bf16 v[130:133], v[134:137], v[194:197], v[130:133]
	v_mfma_f32_16x16x32_bf16 v[126:129], v[142:145], v[194:197], v[126:129]
	v_mfma_f32_16x16x32_bf16 v[114:117], v[134:137], v[202:205], v[114:117]
	v_mfma_f32_16x16x32_bf16 v[110:113], v[142:145], v[202:205], v[110:113]
	v_mfma_f32_16x16x32_bf16 v[98:101], v[134:137], v[210:213], v[98:101]
	v_mfma_f32_16x16x32_bf16 v[94:97], v[142:145], v[210:213], v[94:97]
	v_mfma_f32_16x16x32_bf16 v[82:85], v[134:137], v[218:221], v[82:85]
	v_mfma_f32_16x16x32_bf16 v[78:81], v[142:145], v[218:221], v[78:81]
	v_mfma_f32_16x16x32_bf16 v[130:133], v[138:141], v[198:201], v[130:133]
	v_mfma_f32_16x16x32_bf16 v[126:129], v[146:149], v[198:201], v[126:129]
	v_mfma_f32_16x16x32_bf16 v[114:117], v[138:141], v[206:209], v[114:117]
	v_mfma_f32_16x16x32_bf16 v[110:113], v[146:149], v[206:209], v[110:113]
	v_mfma_f32_16x16x32_bf16 v[98:101], v[138:141], v[214:217], v[98:101]
	v_mfma_f32_16x16x32_bf16 v[94:97], v[146:149], v[214:217], v[94:97]
	v_mfma_f32_16x16x32_bf16 v[82:85], v[138:141], v[222:225], v[82:85]
	v_mfma_f32_16x16x32_bf16 v[78:81], v[146:149], v[222:225], v[78:81]
	v_mfma_f32_16x16x32_bf16 v[122:125], v[150:153], v[194:197], v[122:125]
	v_mfma_f32_16x16x32_bf16 v[118:121], v[186:189], v[194:197], v[118:121]
	v_mfma_f32_16x16x32_bf16 v[106:109], v[150:153], v[202:205], v[106:109]
	v_mfma_f32_16x16x32_bf16 v[102:105], v[186:189], v[202:205], v[102:105]
	v_mfma_f32_16x16x32_bf16 v[90:93], v[150:153], v[210:213], v[90:93]
	v_mfma_f32_16x16x32_bf16 v[86:89], v[186:189], v[210:213], v[86:89]
	v_mfma_f32_16x16x32_bf16 v[74:77], v[150:153], v[218:221], v[74:77]
	v_mfma_f32_16x16x32_bf16 v[70:73], v[186:189], v[218:221], v[70:73]
	v_mfma_f32_16x16x32_bf16 v[122:125], v[154:157], v[198:201], v[122:125]
	v_mfma_f32_16x16x32_bf16 v[118:121], v[190:193], v[198:201], v[118:121]
	v_mfma_f32_16x16x32_bf16 v[106:109], v[154:157], v[206:209], v[106:109]
	v_mfma_f32_16x16x32_bf16 v[102:105], v[190:193], v[206:209], v[102:105]
	v_mfma_f32_16x16x32_bf16 v[90:93], v[154:157], v[214:217], v[90:93]
	v_mfma_f32_16x16x32_bf16 v[86:89], v[190:193], v[214:217], v[86:89]
	v_mfma_f32_16x16x32_bf16 v[74:77], v[154:157], v[222:225], v[74:77]
	v_mfma_f32_16x16x32_bf16 v[70:73], v[190:193], v[222:225], v[70:73]
	s_setprio 0
	s_barrier
	ds_read_b128 v[194:197], v184 offset:16384
	ds_read_b128 v[198:201], v184 offset:17408
	ds_read_b128 v[202:205], v184 offset:18432
	ds_read_b128 v[206:209], v184 offset:19456
	ds_read_b128 v[210:213], v184 offset:20480
	ds_read_b128 v[214:217], v184 offset:21504
	ds_read_b128 v[218:221], v184 offset:22528
	ds_read_b128 v[222:225], v184 offset:23552
	s_mov_b32 m0, s21
	s_nop 0
	global_load_lds_dwordx4 v163, s[30:31]
	s_nop 0
	s_mov_b32 m0, s22
	s_nop 0
	global_load_lds_dwordx4 v181, s[30:31]
	s_add_u32 s24, s30, 0x40000
	s_addc_u32 s25, s31, 0
	s_mov_b32 m0, s23
	s_nop 0
	global_load_lds_dwordx4 v163, s[24:25]
	s_nop 0
	s_mov_b32 m0, s38
	s_nop 0
	global_load_lds_dwordx4 v181, s[24:25]
	s_mov_b32 m0, s20
	s_nop 0
	global_load_lds_dwordx4 v1, s[44:45]
	s_nop 0
	s_mov_b32 m0, s39
	s_nop 0
	global_load_lds_dwordx4 v180, s[44:45]
	s_waitcnt vmcnt(8)
	s_waitcnt lgkmcnt(0)
	s_barrier
	s_setprio 1
	v_mfma_f32_16x16x32_bf16 v[66:69], v[134:137], v[194:197], v[66:69]
	v_mfma_f32_16x16x32_bf16 v[62:65], v[142:145], v[194:197], v[62:65]
	v_mfma_f32_16x16x32_bf16 v[50:53], v[134:137], v[202:205], v[50:53]
	v_mfma_f32_16x16x32_bf16 v[46:49], v[142:145], v[202:205], v[46:49]
	v_mfma_f32_16x16x32_bf16 v[34:37], v[134:137], v[210:213], v[34:37]
	v_mfma_f32_16x16x32_bf16 v[30:33], v[142:145], v[210:213], v[30:33]
	v_mfma_f32_16x16x32_bf16 v[18:21], v[134:137], v[218:221], v[18:21]
	v_mfma_f32_16x16x32_bf16 v[14:17], v[142:145], v[218:221], v[14:17]
	v_mfma_f32_16x16x32_bf16 v[66:69], v[138:141], v[198:201], v[66:69]
	v_mfma_f32_16x16x32_bf16 v[62:65], v[146:149], v[198:201], v[62:65]
	v_mfma_f32_16x16x32_bf16 v[50:53], v[138:141], v[206:209], v[50:53]
	v_mfma_f32_16x16x32_bf16 v[46:49], v[146:149], v[206:209], v[46:49]
	v_mfma_f32_16x16x32_bf16 v[34:37], v[138:141], v[214:217], v[34:37]
	v_mfma_f32_16x16x32_bf16 v[30:33], v[146:149], v[214:217], v[30:33]
	v_mfma_f32_16x16x32_bf16 v[18:21], v[138:141], v[222:225], v[18:21]
	v_mfma_f32_16x16x32_bf16 v[14:17], v[146:149], v[222:225], v[14:17]
	v_mfma_f32_16x16x32_bf16 v[58:61], v[150:153], v[194:197], v[58:61]
	v_mfma_f32_16x16x32_bf16 v[54:57], v[186:189], v[194:197], v[54:57]
	v_mfma_f32_16x16x32_bf16 v[42:45], v[150:153], v[202:205], v[42:45]
	v_mfma_f32_16x16x32_bf16 v[38:41], v[186:189], v[202:205], v[38:41]
	v_mfma_f32_16x16x32_bf16 v[26:29], v[150:153], v[210:213], v[26:29]
	v_mfma_f32_16x16x32_bf16 v[22:25], v[186:189], v[210:213], v[22:25]
	v_mfma_f32_16x16x32_bf16 v[10:13], v[150:153], v[218:221], v[10:13]
	v_mfma_f32_16x16x32_bf16 v[4:7], v[186:189], v[218:221], v[6:9]
	v_mfma_f32_16x16x32_bf16 v[58:61], v[154:157], v[198:201], v[58:61]
	v_mfma_f32_16x16x32_bf16 v[54:57], v[190:193], v[198:201], v[54:57]
	v_mfma_f32_16x16x32_bf16 v[42:45], v[154:157], v[206:209], v[42:45]
	v_mfma_f32_16x16x32_bf16 v[38:41], v[190:193], v[206:209], v[38:41]
	v_mfma_f32_16x16x32_bf16 v[26:29], v[154:157], v[214:217], v[26:29]
	v_mfma_f32_16x16x32_bf16 v[22:25], v[190:193], v[214:217], v[22:25]
	v_mfma_f32_16x16x32_bf16 v[10:13], v[154:157], v[222:225], v[10:13]
	v_mfma_f32_16x16x32_bf16 v[4:7], v[190:193], v[222:225], v[4:7]
	s_setprio 0
	s_barrier
; #define PG8_LDA(dst, b, h) do { _Pragma("unroll") for (int m = 0; m < 4; ++m) _Pragma("unroll") for (int k = 0; k < 2; ++k) dst[m][k] = *(const LAS bf16x8*)(lds + PG8_SA(b, h) + aoff + m * 2048 + k * 1024); } while (0)
; #define PG8_LDB(dst, b, h) do { _Pragma("unroll") for (int n = 0; n < 2; ++n) _Pragma("unroll") for (int k = 0; k < 2; ++k) dst[n][k] = *(const LAS bf16x8*)(lds + PG8_SB(b, h) + boff + n * 2048 + k * 1024); } while (0)
; #define PG8_MMA(ai, bj, At, Bt) do { __builtin_amdgcn_s_setprio(1); _Pragma("unroll") for (int m = 0; m < 4; ++m) _Pragma("unroll") for (int n = 0; n < 2; ++n) _Pragma("unroll") for (int k = 0; k < 2; ++k) \
;         acc[ai][bj][m][n] = __builtin_amdgcn_mfma_f32_16x16x32_bf16(Bt[n][k], At[m][k], acc[ai][bj][m][n], 0, 0, 0); __builtin_amdgcn_s_setprio(0); } while (0)
; #define PG8_WAIT_V(n) asm volatile("s_waitcnt vmcnt(" #n ")" ::: "memory")
; #define PG8_WAIT_L(n) asm volatile("s_waitcnt lgkmcnt(" #n ")" ::: "memory")
; #define PG8_BAR __builtin_amdgcn_s_barrier()
; #define PG8_SCHED __builtin_amdgcn_sched_barrier(0)
; template <class Epi, class Sched>
; __device__ __forceinline__ void gemm_phase(LAS unsigned char* lds, const Gemm g, const Sched& S, const Epi& E) {
;     ...
;             PG8_LDB(B0, 1, 0); PG8_LDB(B1, 1, 1); PG8_SCHED; PG8_LDA(At, 1, 0); PG8_STAGE(PG8_SA(0, 1), a2 + hstepA, voffA);
;             PG8_WAIT_V(8); PG8_WAIT_L(0); PG8_BAR; PG8_MMA(0, 0, At, B0); PG8_MMA(0, 1, At, B1); PG8_BAR; PG8_SCHED;
;             PG8_LDA(At, 1, 1); PG8_STAGE(PG8_SB(1, 0), b3, voffB); PG8_STAGE(PG8_SB(1, 1), b3 + hstepB, voffB); PG8_STAGE(PG8_SA(1, 0), a3, voffA);
;             PG8_WAIT_V(8); PG8_WAIT_L(0); PG8_BAR; PG8_MMA(1, 0, At, B0); PG8_MMA(1, 1, At, B1); PG8_BAR; PG8_SCHED;
;         }
;         if (wr == 0) PG8_BAR;
	v_add_u32_e32 v3, 0x18000, v183
	ds_read_b128 v[134:137], v3
	ds_read_b128 v[138:141], v3 offset:1024
	ds_read_b128 v[142:145], v3 offset:2048
	ds_read_b128 v[146:149], v3 offset:3072
	v_add_u32_e32 v3, 0x1c000, v183
	ds_read_b128 v[150:153], v3
	ds_read_b128 v[154:157], v3 offset:1024
	ds_read_b128 v[186:189], v3 offset:2048
	ds_read_b128 v[190:193], v3 offset:3072
	ds_read_b128 v[194:197], v184 offset:32768
	ds_read_b128 v[198:201], v184 offset:33792
	ds_read_b128 v[202:205], v184 offset:34816
	ds_read_b128 v[206:209], v184 offset:35840
	ds_read_b128 v[210:213], v184 offset:36864
	ds_read_b128 v[214:217], v184 offset:37888
	ds_read_b128 v[218:221], v184 offset:38912
	ds_read_b128 v[222:225], v184 offset:39936
	s_add_u32 s24, s44, 0x20000
	s_addc_u32 s25, s45, 0
	s_mov_b32 m0, s48
	s_nop 0
	global_load_lds_dwordx4 v1, s[24:25]
	s_nop 0
	s_mov_b32 m0, s49
	s_nop 0
	global_load_lds_dwordx4 v180, s[24:25]
	s_waitcnt vmcnt(8)
	s_waitcnt lgkmcnt(0)
	s_barrier
	s_setprio 1
	v_mfma_f32_16x16x32_bf16 v[130:133], v[134:137], v[194:197], v[130:133]
	v_mfma_f32_16x16x32_bf16 v[126:129], v[142:145], v[194:197], v[126:129]
	v_mfma_f32_16x16x32_bf16 v[114:117], v[134:137], v[202:205], v[114:117]
	v_mfma_f32_16x16x32_bf16 v[110:113], v[142:145], v[202:205], v[110:113]
	v_mfma_f32_16x16x32_bf16 v[98:101], v[134:137], v[210:213], v[98:101]
	v_mfma_f32_16x16x32_bf16 v[94:97], v[142:145], v[210:213], v[94:97]
	v_mfma_f32_16x16x32_bf16 v[82:85], v[134:137], v[218:221], v[82:85]
	v_mfma_f32_16x16x32_bf16 v[78:81], v[142:145], v[218:221], v[78:81]
	v_mfma_f32_16x16x32_bf16 v[130:133], v[138:141], v[198:201], v[130:133]
	v_mfma_f32_16x16x32_bf16 v[126:129], v[146:149], v[198:201], v[126:129]
	v_mfma_f32_16x16x32_bf16 v[114:117], v[138:141], v[206:209], v[114:117]
	v_mfma_f32_16x16x32_bf16 v[110:113], v[146:149], v[206:209], v[110:113]
	v_mfma_f32_16x16x32_bf16 v[98:101], v[138:141], v[214:217], v[98:101]
	v_mfma_f32_16x16x32_bf16 v[94:97], v[146:149], v[214:217], v[94:97]
	v_mfma_f32_16x16x32_bf16 v[82:85], v[138:141], v[222:225], v[82:85]
	v_mfma_f32_16x16x32_bf16 v[78:81], v[146:149], v[222:225], v[78:81]
	v_mfma_f32_16x16x32_bf16 v[122:125], v[150:153], v[194:197], v[122:125]
	v_mfma_f32_16x16x32_bf16 v[118:121], v[186:189], v[194:197], v[118:121]
	v_mfma_f32_16x16x32_bf16 v[106:109], v[150:153], v[202:205], v[106:109]
	v_mfma_f32_16x16x32_bf16 v[102:105], v[186:189], v[202:205], v[102:105]
	v_mfma_f32_16x16x32_bf16 v[90:93], v[150:153], v[210:213], v[90:93]
	v_mfma_f32_16x16x32_bf16 v[86:89], v[186:189], v[210:213], v[86:89]
	v_mfma_f32_16x16x32_bf16 v[74:77], v[150:153], v[218:221], v[74:77]
	v_mfma_f32_16x16x32_bf16 v[70:73], v[186:189], v[218:221], v[70:73]
	v_mfma_f32_16x16x32_bf16 v[122:125], v[154:157], v[198:201], v[122:125]
	v_mfma_f32_16x16x32_bf16 v[118:121], v[190:193], v[198:201], v[118:121]
	v_mfma_f32_16x16x32_bf16 v[106:109], v[154:157], v[206:209], v[106:109]
	v_mfma_f32_16x16x32_bf16 v[102:105], v[190:193], v[206:209], v[102:105]
	v_mfma_f32_16x16x32_bf16 v[90:93], v[154:157], v[214:217], v[90:93]
	v_mfma_f32_16x16x32_bf16 v[86:89], v[190:193], v[214:217], v[86:89]
	v_mfma_f32_16x16x32_bf16 v[74:77], v[154:157], v[222:225], v[74:77]
	v_mfma_f32_16x16x32_bf16 v[70:73], v[190:193], v[222:225], v[70:73]
	s_setprio 0
	s_barrier
	ds_read_b128 v[194:197], v184 offset:49152
	ds_read_b128 v[198:201], v184 offset:50176
	ds_read_b128 v[202:205], v184 offset:51200
	ds_read_b128 v[206:209], v184 offset:52224
	ds_read_b128 v[210:213], v184 offset:53248
	ds_read_b128 v[214:217], v184 offset:54272
	ds_read_b128 v[218:221], v184 offset:55296
	ds_read_b128 v[222:225], v184 offset:56320
	s_add_u32 s24, s30, 0x80
	s_addc_u32 s25, s31, 0
	s_mov_b32 m0, s51
	s_nop 0
	global_load_lds_dwordx4 v163, s[24:25]
	s_nop 0
	s_mov_b32 m0, s52
	s_nop 0
	global_load_lds_dwordx4 v181, s[24:25]
	s_add_u32 s24, s30, 0x40080
	s_addc_u32 s25, s31, 0
	s_mov_b32 m0, s57
	s_nop 0
	global_load_lds_dwordx4 v163, s[24:25]
	s_nop 0
	s_mov_b32 m0, s58
	s_nop 0
	global_load_lds_dwordx4 v181, s[24:25]
	s_mov_b32 m0, s53
	s_nop 0
	global_load_lds_dwordx4 v1, s[28:29]
	s_nop 0
	s_mov_b32 m0, s56
	s_nop 0
	global_load_lds_dwordx4 v180, s[28:29]
	s_waitcnt vmcnt(8)
	s_waitcnt lgkmcnt(0)
	s_barrier
	s_setprio 1
	v_mfma_f32_16x16x32_bf16 v[66:69], v[134:137], v[194:197], v[66:69]
	v_mfma_f32_16x16x32_bf16 v[62:65], v[142:145], v[194:197], v[62:65]
	v_mfma_f32_16x16x32_bf16 v[50:53], v[134:137], v[202:205], v[50:53]
	v_mfma_f32_16x16x32_bf16 v[46:49], v[142:145], v[202:205], v[46:49]
	v_mfma_f32_16x16x32_bf16 v[34:37], v[134:137], v[210:213], v[34:37]
	v_mfma_f32_16x16x32_bf16 v[30:33], v[142:145], v[210:213], v[30:33]
	v_mfma_f32_16x16x32_bf16 v[18:21], v[134:137], v[218:221], v[18:21]
	v_mfma_f32_16x16x32_bf16 v[14:17], v[142:145], v[218:221], v[14:17]
	v_mfma_f32_16x16x32_bf16 v[66:69], v[138:141], v[198:201], v[66:69]
	v_mfma_f32_16x16x32_bf16 v[62:65], v[146:149], v[198:201], v[62:65]
	v_mfma_f32_16x16x32_bf16 v[50:53], v[138:141], v[206:209], v[50:53]
	v_mfma_f32_16x16x32_bf16 v[46:49], v[146:149], v[206:209], v[46:49]
	v_mfma_f32_16x16x32_bf16 v[34:37], v[138:141], v[214:217], v[34:37]
	v_mfma_f32_16x16x32_bf16 v[30:33], v[146:149], v[214:217], v[30:33]
	v_mfma_f32_16x16x32_bf16 v[18:21], v[138:141], v[222:225], v[18:21]
	v_mfma_f32_16x16x32_bf16 v[14:17], v[146:149], v[222:225], v[14:17]
	v_mfma_f32_16x16x32_bf16 v[58:61], v[150:153], v[194:197], v[58:61]
	v_mfma_f32_16x16x32_bf16 v[54:57], v[186:189], v[194:197], v[54:57]
	v_mfma_f32_16x16x32_bf16 v[42:45], v[150:153], v[202:205], v[42:45]
	v_mfma_f32_16x16x32_bf16 v[38:41], v[186:189], v[202:205], v[38:41]
	v_mfma_f32_16x16x32_bf16 v[26:29], v[150:153], v[210:213], v[26:29]
	v_mfma_f32_16x16x32_bf16 v[22:25], v[186:189], v[210:213], v[22:25]
	v_mfma_f32_16x16x32_bf16 v[8:11], v[150:153], v[218:221], v[10:13]
	v_mfma_f32_16x16x32_bf16 v[4:7], v[186:189], v[218:221], v[4:7]
	v_mfma_f32_16x16x32_bf16 v[58:61], v[154:157], v[198:201], v[58:61]
	v_mfma_f32_16x16x32_bf16 v[54:57], v[190:193], v[198:201], v[54:57]
	v_mfma_f32_16x16x32_bf16 v[42:45], v[154:157], v[206:209], v[42:45]
	v_mfma_f32_16x16x32_bf16 v[38:41], v[190:193], v[206:209], v[38:41]
	v_mfma_f32_16x16x32_bf16 v[26:29], v[154:157], v[214:217], v[26:29]
	v_mfma_f32_16x16x32_bf16 v[22:25], v[190:193], v[214:217], v[22:25]
	v_mfma_f32_16x16x32_bf16 v[10:13], v[154:157], v[222:225], v[8:11]
	v_mfma_f32_16x16x32_bf16 v[6:9], v[190:193], v[222:225], v[4:7]
	s_setprio 0
	s_barrier
	s_add_i32 s66, s66, 2
	s_add_u32 s64, s64, 0x100
	s_addc_u32 s65, s65, 0
	s_cmp_gt_u32 s66, 13
	s_cbranch_scc0 .LBB0_616
	s_and_b64 vcc, exec, s[10:11]
	s_cbranch_vccz .LBB0_621
	s_barrier

; #define PG8_LDA(dst, b, h) do { _Pragma("unroll") for (int m = 0; m < 4; ++m) _Pragma("unroll") for (int k = 0; k < 2; ++k) dst[m][k] = *(const LAS bf16x8*)(lds + PG8_SA(b, h) + aoff + m * 2048 + k * 1024); } while (0)
; #define PG8_LDB(dst, b, h) do { _Pragma("unroll") for (int n = 0; n < 2; ++n) _Pragma("unroll") for (int k = 0; k < 2; ++k) dst[n][k] = *(const LAS bf16x8*)(lds + PG8_SB(b, h) + boff + n * 2048 + k * 1024); } while (0)
; #define PG8_MMA(ai, bj, At, Bt) do { __builtin_amdgcn_s_setprio(1); _Pragma("unroll") for (int m = 0; m < 4; ++m) _Pragma("unroll") for (int n = 0; n < 2; ++n) _Pragma("unroll") for (int k = 0; k < 2; ++k) \
;         acc[ai][bj][m][n] = __builtin_amdgcn_mfma_f32_16x16x32_bf16(Bt[n][k], At[m][k], acc[ai][bj][m][n], 0, 0, 0); __builtin_amdgcn_s_setprio(0); } while (0)
; #define PG8_WAIT_V(n) asm volatile("s_waitcnt vmcnt(" #n ")" ::: "memory")
; #define PG8_WAIT_L(n) asm volatile("s_waitcnt lgkmcnt(" #n ")" ::: "memory")
; #define PG8_BAR __builtin_amdgcn_s_barrier()
; #define PG8_SCHED __builtin_amdgcn_sched_barrier(0)
; template <class Epi, class Sched>
; __device__ __forceinline__ void gemm_phase(LAS unsigned char* lds, const Gemm g, const Sched& S, const Epi& E) {
;     ...
;             PG8_LDB(B0, 0, 0); PG8_LDB(B1, 0, 1); PG8_SCHED; PG8_LDA(At, 0, 0); PG8_STAGE(PG8_SA(1, 1), a1 + hstepA, voffA);
;             PG8_WAIT_V(8); PG8_WAIT_L(0); PG8_BAR; PG8_MMA(0, 0, At, B0); PG8_MMA(0, 1, At, B1); PG8_BAR; PG8_SCHED;
;             PG8_LDA(At, 0, 1); PG8_STAGE(PG8_SB(0, 0), b2, voffB); PG8_STAGE(PG8_SB(0, 1), b2 + hstepB, voffB); PG8_STAGE(PG8_SA(0, 0), a2, voffA);
;             PG8_WAIT_V(8); PG8_WAIT_L(0); PG8_BAR; PG8_MMA(1, 0, At, B0); PG8_MMA(1, 1, At, B1); PG8_BAR; PG8_SCHED;
.LBB0_712:
	v_add_u32_e32 v162, 0x10000, v169
	ds_read_b128 v[172:175], v162
	ds_read_b128 v[176:179], v162 offset:1024
	ds_read_b128 v[180:183], v162 offset:2048
	ds_read_b128 v[184:187], v162 offset:3072
	v_add_u32_e32 v162, 0x14000, v169
	ds_read_b128 v[188:191], v162
	ds_read_b128 v[192:195], v162 offset:1024
	ds_read_b128 v[196:199], v162 offset:2048
	ds_read_b128 v[200:203], v162 offset:3072
	s_add_u32 vcc_lo, s6, 0x100
	s_addc_u32 vcc_hi, s7, 0
	s_cmp_eq_u32 s73, 12
	s_cselect_b32 s18, s11, vcc_lo
	s_cselect_b32 s19, s1, vcc_hi
	s_cselect_b32 s16, s44, s45
	s_cselect_b32 s17, s5, s72
	s_add_u32 s14, s18, 0x80
	s_addc_u32 s15, s19, 0
	ds_read_b128 v[204:207], v170
	ds_read_b128 v[208:211], v170 offset:1024
	ds_read_b128 v[212:215], v170 offset:2048
	ds_read_b128 v[216:219], v170 offset:3072
	ds_read_b128 v[220:223], v170 offset:4096
	ds_read_b128 v[224:227], v170 offset:5120
	ds_read_b128 v[228:231], v170 offset:6144
	ds_read_b128 v[232:235], v170 offset:7168
	s_add_u32 s6, s6, 0x20080
	s_addc_u32 s7, s7, 0
	s_mov_b32 m0, s24
	s_nop 0
	global_load_lds_dwordx4 v165, s[6:7]
	s_add_i32 s74, s35, 0xe000
	s_mov_b32 m0, s74
	s_nop 0
	global_load_lds_dwordx4 v167, s[6:7]
	s_waitcnt vmcnt(8)
	s_waitcnt lgkmcnt(0)
	s_barrier
	s_setprio 1
	v_mfma_f32_16x16x32_bf16 v[126:129], v[172:175], v[204:207], v[126:129]
	v_mfma_f32_16x16x32_bf16 v[122:125], v[180:183], v[204:207], v[122:125]
	v_mfma_f32_16x16x32_bf16 v[110:113], v[172:175], v[212:215], v[110:113]
	v_mfma_f32_16x16x32_bf16 v[106:109], v[180:183], v[212:215], v[106:109]
	v_mfma_f32_16x16x32_bf16 v[94:97], v[172:175], v[220:223], v[94:97]
	v_mfma_f32_16x16x32_bf16 v[90:93], v[180:183], v[220:223], v[90:93]
	v_mfma_f32_16x16x32_bf16 v[78:81], v[172:175], v[228:231], v[78:81]
	v_mfma_f32_16x16x32_bf16 v[74:77], v[180:183], v[228:231], v[74:77]
	v_mfma_f32_16x16x32_bf16 v[126:129], v[176:179], v[208:211], v[126:129]
	v_mfma_f32_16x16x32_bf16 v[122:125], v[184:187], v[208:211], v[122:125]
	v_mfma_f32_16x16x32_bf16 v[110:113], v[176:179], v[216:219], v[110:113]
	v_mfma_f32_16x16x32_bf16 v[106:109], v[184:187], v[216:219], v[106:109]
	v_mfma_f32_16x16x32_bf16 v[94:97], v[176:179], v[224:227], v[94:97]
	v_mfma_f32_16x16x32_bf16 v[90:93], v[184:187], v[224:227], v[90:93]
	v_mfma_f32_16x16x32_bf16 v[78:81], v[176:179], v[232:235], v[78:81]
	v_mfma_f32_16x16x32_bf16 v[74:77], v[184:187], v[232:235], v[74:77]
	v_mfma_f32_16x16x32_bf16 v[118:121], v[188:191], v[204:207], v[118:121]
	v_mfma_f32_16x16x32_bf16 v[114:117], v[196:199], v[204:207], v[114:117]
	v_mfma_f32_16x16x32_bf16 v[102:105], v[188:191], v[212:215], v[102:105]
	v_mfma_f32_16x16x32_bf16 v[98:101], v[196:199], v[212:215], v[98:101]
	v_mfma_f32_16x16x32_bf16 v[86:89], v[188:191], v[220:223], v[86:89]
	v_mfma_f32_16x16x32_bf16 v[82:85], v[196:199], v[220:223], v[82:85]
	v_mfma_f32_16x16x32_bf16 v[70:73], v[188:191], v[228:231], v[70:73]
	v_mfma_f32_16x16x32_bf16 v[66:69], v[196:199], v[228:231], v[66:69]
	v_mfma_f32_16x16x32_bf16 v[118:121], v[192:195], v[208:211], v[118:121]
	v_mfma_f32_16x16x32_bf16 v[114:117], v[200:203], v[208:211], v[114:117]
	v_mfma_f32_16x16x32_bf16 v[102:105], v[192:195], v[216:219], v[102:105]
	v_mfma_f32_16x16x32_bf16 v[98:101], v[200:203], v[216:219], v[98:101]
	v_mfma_f32_16x16x32_bf16 v[86:89], v[192:195], v[224:227], v[86:89]
	v_mfma_f32_16x16x32_bf16 v[82:85], v[200:203], v[224:227], v[82:85]
	v_mfma_f32_16x16x32_bf16 v[70:73], v[192:195], v[232:235], v[70:73]
	v_mfma_f32_16x16x32_bf16 v[66:69], v[200:203], v[232:235], v[66:69]
	s_setprio 0
	s_barrier
	ds_read_b128 v[204:207], v170 offset:16384
	ds_read_b128 v[208:211], v170 offset:17408
	ds_read_b128 v[212:215], v170 offset:18432
	ds_read_b128 v[216:219], v170 offset:19456
	ds_read_b128 v[220:223], v170 offset:20480
	ds_read_b128 v[224:227], v170 offset:21504
	ds_read_b128 v[228:231], v170 offset:22528
	ds_read_b128 v[232:235], v170 offset:23552
	s_mov_b32 m0, s64
	s_nop 0
	global_load_lds_dwordx4 v166, s[16:17]
	s_nop 0
	s_mov_b32 m0, s65
	s_nop 0
	global_load_lds_dwordx4 v168, s[16:17]
	s_add_u32 s6, s16, 0x40000
	s_addc_u32 s7, s17, 0
	s_mov_b32 m0, s38
	s_nop 0
	global_load_lds_dwordx4 v166, s[6:7]
	s_nop 0
	s_mov_b32 m0, s39
	s_nop 0
	global_load_lds_dwordx4 v168, s[6:7]
	s_mov_b32 m0, s35
	s_nop 0
	global_load_lds_dwordx4 v165, s[18:19]
	s_nop 0
	s_mov_b32 m0, s48
	s_nop 0
	global_load_lds_dwordx4 v167, s[18:19]
	s_waitcnt vmcnt(8)
	s_waitcnt lgkmcnt(0)
	s_barrier
	s_setprio 1
	v_mfma_f32_16x16x32_bf16 v[62:65], v[172:175], v[204:207], v[62:65]
	v_mfma_f32_16x16x32_bf16 v[58:61], v[180:183], v[204:207], v[58:61]
	v_mfma_f32_16x16x32_bf16 v[46:49], v[172:175], v[212:215], v[46:49]
	v_mfma_f32_16x16x32_bf16 v[42:45], v[180:183], v[212:215], v[42:45]
	v_mfma_f32_16x16x32_bf16 v[30:33], v[172:175], v[220:223], v[30:33]
	v_mfma_f32_16x16x32_bf16 v[26:29], v[180:183], v[220:223], v[26:29]
	v_mfma_f32_16x16x32_bf16 v[14:17], v[172:175], v[228:231], v[14:17]
	v_mfma_f32_16x16x32_bf16 v[10:13], v[180:183], v[228:231], v[10:13]
	v_mfma_f32_16x16x32_bf16 v[62:65], v[176:179], v[208:211], v[62:65]
	v_mfma_f32_16x16x32_bf16 v[58:61], v[184:187], v[208:211], v[58:61]
	v_mfma_f32_16x16x32_bf16 v[46:49], v[176:179], v[216:219], v[46:49]
	v_mfma_f32_16x16x32_bf16 v[42:45], v[184:187], v[216:219], v[42:45]
	v_mfma_f32_16x16x32_bf16 v[30:33], v[176:179], v[224:227], v[30:33]
	v_mfma_f32_16x16x32_bf16 v[26:29], v[184:187], v[224:227], v[26:29]
	v_mfma_f32_16x16x32_bf16 v[14:17], v[176:179], v[232:235], v[14:17]
	v_mfma_f32_16x16x32_bf16 v[10:13], v[184:187], v[232:235], v[10:13]
	v_mfma_f32_16x16x32_bf16 v[54:57], v[188:191], v[204:207], v[54:57]
	v_mfma_f32_16x16x32_bf16 v[50:53], v[196:199], v[204:207], v[50:53]
	v_mfma_f32_16x16x32_bf16 v[38:41], v[188:191], v[212:215], v[38:41]
	v_mfma_f32_16x16x32_bf16 v[34:37], v[196:199], v[212:215], v[34:37]
	v_mfma_f32_16x16x32_bf16 v[22:25], v[188:191], v[220:223], v[22:25]
	v_mfma_f32_16x16x32_bf16 v[18:21], v[196:199], v[220:223], v[18:21]
	v_mfma_f32_16x16x32_bf16 v[6:9], v[188:191], v[228:231], v[6:9]
	v_mfma_f32_16x16x32_bf16 v[2:5], v[196:199], v[228:231], v[2:5]
	v_mfma_f32_16x16x32_bf16 v[54:57], v[192:195], v[208:211], v[54:57]
	v_mfma_f32_16x16x32_bf16 v[50:53], v[200:203], v[208:211], v[50:53]
	v_mfma_f32_16x16x32_bf16 v[38:41], v[192:195], v[216:219], v[38:41]
	v_mfma_f32_16x16x32_bf16 v[34:37], v[200:203], v[216:219], v[34:37]
	v_mfma_f32_16x16x32_bf16 v[22:25], v[192:195], v[224:227], v[22:25]
	v_mfma_f32_16x16x32_bf16 v[18:21], v[200:203], v[224:227], v[18:21]
	v_mfma_f32_16x16x32_bf16 v[6:9], v[192:195], v[232:235], v[6:9]
	v_mfma_f32_16x16x32_bf16 v[2:5], v[200:203], v[232:235], v[2:5]
	s_setprio 0
	s_barrier
; #define PG8_LDA(dst, b, h) do { _Pragma("unroll") for (int m = 0; m < 4; ++m) _Pragma("unroll") for (int k = 0; k < 2; ++k) dst[m][k] = *(const LAS bf16x8*)(lds + PG8_SA(b, h) + aoff + m * 2048 + k * 1024); } while (0)
; #define PG8_LDB(dst, b, h) do { _Pragma("unroll") for (int n = 0; n < 2; ++n) _Pragma("unroll") for (int k = 0; k < 2; ++k) dst[n][k] = *(const LAS bf16x8*)(lds + PG8_SB(b, h) + boff + n * 2048 + k * 1024); } while (0)
; #define PG8_MMA(ai, bj, At, Bt) do { __builtin_amdgcn_s_setprio(1); _Pragma("unroll") for (int m = 0; m < 4; ++m) _Pragma("unroll") for (int n = 0; n < 2; ++n) _Pragma("unroll") for (int k = 0; k < 2; ++k) \
;         acc[ai][bj][m][n] = __builtin_amdgcn_mfma_f32_16x16x32_bf16(Bt[n][k], At[m][k], acc[ai][bj][m][n], 0, 0, 0); __builtin_amdgcn_s_setprio(0); } while (0)
; #define PG8_WAIT_V(n) asm volatile("s_waitcnt vmcnt(" #n ")" ::: "memory")
; #define PG8_WAIT_L(n) asm volatile("s_waitcnt lgkmcnt(" #n ")" ::: "memory")
; #define PG8_BAR __builtin_amdgcn_s_barrier()
; #define PG8_SCHED __builtin_amdgcn_sched_barrier(0)
; template <class Epi, class Sched>
; __device__ __forceinline__ void gemm_phase(LAS unsigned char* lds, const Gemm g, const Sched& S, const Epi& E) {
;     ...
;             PG8_LDB(B0, 1, 0); PG8_LDB(B1, 1, 1); PG8_SCHED; PG8_LDA(At, 1, 0); PG8_STAGE(PG8_SA(0, 1), a2 + hstepA, voffA);
;             PG8_WAIT_V(8); PG8_WAIT_L(0); PG8_BAR; PG8_MMA(0, 0, At, B0); PG8_MMA(0, 1, At, B1); PG8_BAR; PG8_SCHED;
;             PG8_LDA(At, 1, 1); PG8_STAGE(PG8_SB(1, 0), b3, voffB); PG8_STAGE(PG8_SB(1, 1), b3 + hstepB, voffB); PG8_STAGE(PG8_SA(1, 0), a3, voffA);
;             PG8_WAIT_V(8); PG8_WAIT_L(0); PG8_BAR; PG8_MMA(1, 0, At, B0); PG8_MMA(1, 1, At, B1); PG8_BAR; PG8_SCHED;
;         }
;         if (wr == 0) PG8_BAR;
	v_add_u32_e32 v162, 0x18000, v169
	ds_read_b128 v[172:175], v162
	ds_read_b128 v[176:179], v162 offset:1024
	ds_read_b128 v[180:183], v162 offset:2048
	ds_read_b128 v[184:187], v162 offset:3072
	v_add_u32_e32 v162, 0x1c000, v169
	ds_read_b128 v[188:191], v162
	ds_read_b128 v[192:195], v162 offset:1024
	ds_read_b128 v[196:199], v162 offset:2048
	ds_read_b128 v[200:203], v162 offset:3072
	ds_read_b128 v[204:207], v170 offset:32768
	ds_read_b128 v[208:211], v170 offset:33792
	ds_read_b128 v[212:215], v170 offset:34816
	ds_read_b128 v[216:219], v170 offset:35840
	ds_read_b128 v[220:223], v170 offset:36864
	ds_read_b128 v[224:227], v170 offset:37888
	ds_read_b128 v[228:231], v170 offset:38912
	ds_read_b128 v[232:235], v170 offset:39936
	s_add_u32 s6, s18, 0x20000
	s_addc_u32 s7, s19, 0
	s_mov_b32 m0, s49
	s_nop 0
	global_load_lds_dwordx4 v165, s[6:7]
	s_nop 0
	s_mov_b32 m0, s25
	s_nop 0
	global_load_lds_dwordx4 v167, s[6:7]
	s_waitcnt vmcnt(8)
	s_waitcnt lgkmcnt(0)
	s_barrier
	s_setprio 1
	v_mfma_f32_16x16x32_bf16 v[126:129], v[172:175], v[204:207], v[126:129]
	v_mfma_f32_16x16x32_bf16 v[122:125], v[180:183], v[204:207], v[122:125]
	v_mfma_f32_16x16x32_bf16 v[110:113], v[172:175], v[212:215], v[110:113]
	v_mfma_f32_16x16x32_bf16 v[106:109], v[180:183], v[212:215], v[106:109]
	v_mfma_f32_16x16x32_bf16 v[94:97], v[172:175], v[220:223], v[94:97]
	v_mfma_f32_16x16x32_bf16 v[90:93], v[180:183], v[220:223], v[90:93]
	v_mfma_f32_16x16x32_bf16 v[78:81], v[172:175], v[228:231], v[78:81]
	v_mfma_f32_16x16x32_bf16 v[74:77], v[180:183], v[228:231], v[74:77]
	v_mfma_f32_16x16x32_bf16 v[126:129], v[176:179], v[208:211], v[126:129]
	v_mfma_f32_16x16x32_bf16 v[122:125], v[184:187], v[208:211], v[122:125]
	v_mfma_f32_16x16x32_bf16 v[110:113], v[176:179], v[216:219], v[110:113]
	v_mfma_f32_16x16x32_bf16 v[106:109], v[184:187], v[216:219], v[106:109]
	v_mfma_f32_16x16x32_bf16 v[94:97], v[176:179], v[224:227], v[94:97]
	v_mfma_f32_16x16x32_bf16 v[90:93], v[184:187], v[224:227], v[90:93]
	v_mfma_f32_16x16x32_bf16 v[78:81], v[176:179], v[232:235], v[78:81]
	v_mfma_f32_16x16x32_bf16 v[74:77], v[184:187], v[232:235], v[74:77]
	v_mfma_f32_16x16x32_bf16 v[118:121], v[188:191], v[204:207], v[118:121]
	v_mfma_f32_16x16x32_bf16 v[114:117], v[196:199], v[204:207], v[114:117]
	v_mfma_f32_16x16x32_bf16 v[102:105], v[188:191], v[212:215], v[102:105]
	v_mfma_f32_16x16x32_bf16 v[98:101], v[196:199], v[212:215], v[98:101]
	v_mfma_f32_16x16x32_bf16 v[86:89], v[188:191], v[220:223], v[86:89]
	v_mfma_f32_16x16x32_bf16 v[82:85], v[196:199], v[220:223], v[82:85]
	v_mfma_f32_16x16x32_bf16 v[70:73], v[188:191], v[228:231], v[70:73]
	v_mfma_f32_16x16x32_bf16 v[66:69], v[196:199], v[228:231], v[66:69]
	v_mfma_f32_16x16x32_bf16 v[118:121], v[192:195], v[208:211], v[118:121]
	v_mfma_f32_16x16x32_bf16 v[114:117], v[200:203], v[208:211], v[114:117]
	v_mfma_f32_16x16x32_bf16 v[102:105], v[192:195], v[216:219], v[102:105]
	v_mfma_f32_16x16x32_bf16 v[98:101], v[200:203], v[216:219], v[98:101]
	v_mfma_f32_16x16x32_bf16 v[86:89], v[192:195], v[224:227], v[86:89]
	v_mfma_f32_16x16x32_bf16 v[82:85], v[200:203], v[224:227], v[82:85]
	v_mfma_f32_16x16x32_bf16 v[70:73], v[192:195], v[232:235], v[70:73]
	v_mfma_f32_16x16x32_bf16 v[66:69], v[200:203], v[232:235], v[66:69]
	s_setprio 0
	s_barrier
	ds_read_b128 v[204:207], v170 offset:49152
	ds_read_b128 v[208:211], v170 offset:50176
	ds_read_b128 v[212:215], v170 offset:51200
	ds_read_b128 v[216:219], v170 offset:52224
	ds_read_b128 v[220:223], v170 offset:53248
	ds_read_b128 v[224:227], v170 offset:54272
	ds_read_b128 v[228:231], v170 offset:55296
	ds_read_b128 v[232:235], v170 offset:56320
	s_add_u32 s6, s16, 0x80
	s_addc_u32 s7, s17, 0
	s_mov_b32 m0, s26
	s_nop 0
	global_load_lds_dwordx4 v166, s[6:7]
	s_nop 0
	s_mov_b32 m0, s30
	s_nop 0
	global_load_lds_dwordx4 v168, s[6:7]
	s_add_u32 s6, s16, 0x40080
	s_addc_u32 s7, s17, 0
	s_mov_b32 m0, s23
	s_nop 0
	global_load_lds_dwordx4 v166, s[6:7]
	s_nop 0
	s_mov_b32 m0, s22
	s_nop 0
	global_load_lds_dwordx4 v168, s[6:7]
	s_mov_b32 m0, s31
	s_nop 0
	global_load_lds_dwordx4 v165, s[14:15]
	s_nop 0
	s_mov_b32 m0, s21
	s_nop 0
	global_load_lds_dwordx4 v167, s[14:15]
	s_waitcnt vmcnt(8)
	s_waitcnt lgkmcnt(0)
	s_barrier
	s_setprio 1
	v_mfma_f32_16x16x32_bf16 v[62:65], v[172:175], v[204:207], v[62:65]
	v_mfma_f32_16x16x32_bf16 v[58:61], v[180:183], v[204:207], v[58:61]
	v_mfma_f32_16x16x32_bf16 v[46:49], v[172:175], v[212:215], v[46:49]
	v_mfma_f32_16x16x32_bf16 v[42:45], v[180:183], v[212:215], v[42:45]
	v_mfma_f32_16x16x32_bf16 v[30:33], v[172:175], v[220:223], v[30:33]
	v_mfma_f32_16x16x32_bf16 v[26:29], v[180:183], v[220:223], v[26:29]
	v_mfma_f32_16x16x32_bf16 v[14:17], v[172:175], v[228:231], v[14:17]
	v_mfma_f32_16x16x32_bf16 v[10:13], v[180:183], v[228:231], v[10:13]
	v_mfma_f32_16x16x32_bf16 v[62:65], v[176:179], v[208:211], v[62:65]
	v_mfma_f32_16x16x32_bf16 v[58:61], v[184:187], v[208:211], v[58:61]
	v_mfma_f32_16x16x32_bf16 v[46:49], v[176:179], v[216:219], v[46:49]
	v_mfma_f32_16x16x32_bf16 v[42:45], v[184:187], v[216:219], v[42:45]
	v_mfma_f32_16x16x32_bf16 v[30:33], v[176:179], v[224:227], v[30:33]
	v_mfma_f32_16x16x32_bf16 v[26:29], v[184:187], v[224:227], v[26:29]
	v_mfma_f32_16x16x32_bf16 v[14:17], v[176:179], v[232:235], v[14:17]
	v_mfma_f32_16x16x32_bf16 v[10:13], v[184:187], v[232:235], v[10:13]
	v_mfma_f32_16x16x32_bf16 v[54:57], v[188:191], v[204:207], v[54:57]
	v_mfma_f32_16x16x32_bf16 v[50:53], v[196:199], v[204:207], v[50:53]
	v_mfma_f32_16x16x32_bf16 v[38:41], v[188:191], v[212:215], v[38:41]
	v_mfma_f32_16x16x32_bf16 v[34:37], v[196:199], v[212:215], v[34:37]
	v_mfma_f32_16x16x32_bf16 v[22:25], v[188:191], v[220:223], v[22:25]
	v_mfma_f32_16x16x32_bf16 v[18:21], v[196:199], v[220:223], v[18:21]
	v_mfma_f32_16x16x32_bf16 v[6:9], v[188:191], v[228:231], v[6:9]
	v_mfma_f32_16x16x32_bf16 v[2:5], v[196:199], v[228:231], v[2:5]
	v_mfma_f32_16x16x32_bf16 v[54:57], v[192:195], v[208:211], v[54:57]
	v_mfma_f32_16x16x32_bf16 v[50:53], v[200:203], v[208:211], v[50:53]
	v_mfma_f32_16x16x32_bf16 v[38:41], v[192:195], v[216:219], v[38:41]
	v_mfma_f32_16x16x32_bf16 v[34:37], v[200:203], v[216:219], v[34:37]
	v_mfma_f32_16x16x32_bf16 v[22:25], v[192:195], v[224:227], v[22:25]
	v_mfma_f32_16x16x32_bf16 v[18:21], v[200:203], v[224:227], v[18:21]
	v_mfma_f32_16x16x32_bf16 v[6:9], v[192:195], v[232:235], v[6:9]
	v_mfma_f32_16x16x32_bf16 v[2:5], v[200:203], v[232:235], v[2:5]
	s_setprio 0
	s_barrier
	s_add_i32 s73, s73, 2
	s_add_u32 s45, s45, 0x100
	s_addc_u32 s72, s72, 0
	s_cmp_gt_u32 s73, 13
	s_mov_b64 s[6:7], vcc
	s_cbranch_scc0 .LBB0_712
	s_and_b64 vcc, exec, s[98:99]
	s_cbranch_vccz .LBB0_715
	s_barrier

; #define PG8_LDA(dst, b, h) do { _Pragma("unroll") for (int m = 0; m < 4; ++m) _Pragma("unroll") for (int k = 0; k < 2; ++k) dst[m][k] = *(const LAS bf16x8*)(lds + PG8_SA(b, h) + aoff + m * 2048 + k * 1024); } while (0)
; #define PG8_LDB(dst, b, h) do { _Pragma("unroll") for (int n = 0; n < 2; ++n) _Pragma("unroll") for (int k = 0; k < 2; ++k) dst[n][k] = *(const LAS bf16x8*)(lds + PG8_SB(b, h) + boff + n * 2048 + k * 1024); } while (0)
; #define PG8_MMA(ai, bj, At, Bt) do { __builtin_amdgcn_s_setprio(1); _Pragma("unroll") for (int m = 0; m < 4; ++m) _Pragma("unroll") for (int n = 0; n < 2; ++n) _Pragma("unroll") for (int k = 0; k < 2; ++k) \
;         acc[ai][bj][m][n] = __builtin_amdgcn_mfma_f32_16x16x32_bf16(Bt[n][k], At[m][k], acc[ai][bj][m][n], 0, 0, 0); __builtin_amdgcn_s_setprio(0); } while (0)
; #define PG8_WAIT_V(n) asm volatile("s_waitcnt vmcnt(" #n ")" ::: "memory")
; #define PG8_WAIT_L(n) asm volatile("s_waitcnt lgkmcnt(" #n ")" ::: "memory")
; #define PG8_BAR __builtin_amdgcn_s_barrier()
; #define PG8_SCHED __builtin_amdgcn_sched_barrier(0)
; template <class Epi, class Sched>
; __device__ __forceinline__ void gemm_phase(LAS unsigned char* lds, const Gemm g, const Sched& S, const Epi& E) {
;     ...
;             const bool last = (t == nt - 2);
;             if constexpr (Epi::MID) { if (t == nt / 2) E.mid(acc, cur, wr, wc, fr, fq); }
;             const char* a1 = cA + (size_t)(t + 1) * kstepA;
;             const char* a2 = last ? nA : cA + (size_t)(t + 2) * kstepA; const char* b2 = last ? nB : cB + (size_t)(t + 2) * kstep;
;             const char* a3 = a2 + kstepA; const char* b3 = b2 + kstep;
;             PG8_LDB(B0, 0, 0); PG8_LDB(B1, 0, 1); PG8_SCHED; PG8_LDA(At, 0, 0); PG8_STAGE(PG8_SA(1, 1), a1 + hstepA, voffA);
;             PG8_WAIT_V(8); PG8_WAIT_L(0); PG8_BAR; PG8_MMA(0, 0, At, B0); PG8_MMA(0, 1, At, B1); PG8_BAR; PG8_SCHED;
;             PG8_LDA(At, 0, 1); PG8_STAGE(PG8_SB(0, 0), b2, voffB); PG8_STAGE(PG8_SB(0, 1), b2 + hstepB, voffB); PG8_STAGE(PG8_SA(0, 0), a2, voffA);
;             PG8_WAIT_V(8); PG8_WAIT_L(0); PG8_BAR; PG8_MMA(1, 0, At, B0); PG8_MMA(1, 1, At, B1); PG8_BAR; PG8_SCHED;
.LBB0_780:
	v_add_u32_e32 v146, 0x10000, v152
	ds_read_b128 v[154:157], v146
	ds_read_b128 v[158:161], v146 offset:1024
	ds_read_b128 v[166:169], v146 offset:2048
	ds_read_b128 v[170:173], v146 offset:3072
	v_add_u32_e32 v146, 0x14000, v152
	ds_read_b128 v[174:177], v146
	ds_read_b128 v[178:181], v146 offset:1024
	ds_read_b128 v[182:185], v146 offset:2048
	ds_read_b128 v[186:189], v146 offset:3072
	s_add_u32 s98, s12, 0x10000
	s_addc_u32 s99, s13, 0
	s_cmp_eq_u32 s73, 60
	s_cselect_b32 s18, s65, s98
	s_cselect_b32 s19, s9, s99
	s_cselect_b32 s16, s44, s45
	s_cselect_b32 s17, s11, s72
	s_add_u32 s14, s18, 0x8000
	s_addc_u32 s15, s19, 0
	ds_read_b128 v[190:193], v153
	ds_read_b128 v[194:197], v153 offset:1024
	ds_read_b128 v[198:201], v153 offset:2048
	ds_read_b128 v[202:205], v153 offset:3072
	ds_read_b128 v[206:209], v153 offset:4096
	ds_read_b128 v[210:213], v153 offset:5120
	ds_read_b128 v[214:217], v153 offset:6144
	ds_read_b128 v[218:221], v153 offset:7168
	s_add_u32 s12, s12, 0xa000
	s_addc_u32 s13, s13, 0
	s_mov_b32 m0, s62
	s_nop 0
	global_load_lds_dwordx4 v148, s[12:13]
	s_add_i32 s74, s21, 0xe000
	s_mov_b32 m0, s74
	s_nop 0
	global_load_lds_dwordx4 v150, s[12:13]
	s_waitcnt vmcnt(8)
	s_waitcnt lgkmcnt(0)
	s_barrier
	s_setprio 1
	v_mfma_f32_16x16x32_bf16 v[126:129], v[154:157], v[190:193], v[126:129]
	v_mfma_f32_16x16x32_bf16 v[122:125], v[166:169], v[190:193], v[122:125]
	v_mfma_f32_16x16x32_bf16 v[110:113], v[154:157], v[198:201], v[110:113]
	v_mfma_f32_16x16x32_bf16 v[106:109], v[166:169], v[198:201], v[106:109]
	v_mfma_f32_16x16x32_bf16 v[94:97], v[154:157], v[206:209], v[94:97]
	v_mfma_f32_16x16x32_bf16 v[90:93], v[166:169], v[206:209], v[90:93]
	v_mfma_f32_16x16x32_bf16 v[78:81], v[154:157], v[214:217], v[78:81]
	v_mfma_f32_16x16x32_bf16 v[74:77], v[166:169], v[214:217], v[74:77]
	v_mfma_f32_16x16x32_bf16 v[126:129], v[158:161], v[194:197], v[126:129]
	v_mfma_f32_16x16x32_bf16 v[122:125], v[170:173], v[194:197], v[122:125]
	v_mfma_f32_16x16x32_bf16 v[110:113], v[158:161], v[202:205], v[110:113]
	v_mfma_f32_16x16x32_bf16 v[106:109], v[170:173], v[202:205], v[106:109]
	v_mfma_f32_16x16x32_bf16 v[94:97], v[158:161], v[210:213], v[94:97]
	v_mfma_f32_16x16x32_bf16 v[90:93], v[170:173], v[210:213], v[90:93]
	v_mfma_f32_16x16x32_bf16 v[78:81], v[158:161], v[218:221], v[78:81]
	v_mfma_f32_16x16x32_bf16 v[74:77], v[170:173], v[218:221], v[74:77]
	v_mfma_f32_16x16x32_bf16 v[118:121], v[174:177], v[190:193], v[118:121]
	v_mfma_f32_16x16x32_bf16 v[114:117], v[182:185], v[190:193], v[114:117]
	v_mfma_f32_16x16x32_bf16 v[102:105], v[174:177], v[198:201], v[102:105]
	v_mfma_f32_16x16x32_bf16 v[98:101], v[182:185], v[198:201], v[98:101]
	v_mfma_f32_16x16x32_bf16 v[86:89], v[174:177], v[206:209], v[86:89]
	v_mfma_f32_16x16x32_bf16 v[82:85], v[182:185], v[206:209], v[82:85]
	v_mfma_f32_16x16x32_bf16 v[70:73], v[174:177], v[214:217], v[70:73]
	v_mfma_f32_16x16x32_bf16 v[66:69], v[182:185], v[214:217], v[66:69]
	v_mfma_f32_16x16x32_bf16 v[118:121], v[178:181], v[194:197], v[118:121]
	v_mfma_f32_16x16x32_bf16 v[114:117], v[186:189], v[194:197], v[114:117]
	v_mfma_f32_16x16x32_bf16 v[102:105], v[178:181], v[202:205], v[102:105]
	v_mfma_f32_16x16x32_bf16 v[98:101], v[186:189], v[202:205], v[98:101]
	v_mfma_f32_16x16x32_bf16 v[86:89], v[178:181], v[210:213], v[86:89]
	v_mfma_f32_16x16x32_bf16 v[82:85], v[186:189], v[210:213], v[82:85]
	v_mfma_f32_16x16x32_bf16 v[70:73], v[178:181], v[218:221], v[70:73]
	v_mfma_f32_16x16x32_bf16 v[66:69], v[186:189], v[218:221], v[66:69]
	s_setprio 0
	s_barrier
	ds_read_b128 v[190:193], v153 offset:16384
	ds_read_b128 v[194:197], v153 offset:17408
	ds_read_b128 v[198:201], v153 offset:18432
	ds_read_b128 v[202:205], v153 offset:19456
	ds_read_b128 v[206:209], v153 offset:20480
	ds_read_b128 v[210:213], v153 offset:21504
	ds_read_b128 v[214:217], v153 offset:22528
	ds_read_b128 v[218:221], v153 offset:23552
	s_mov_b32 m0, s22
	s_nop 0
	global_load_lds_dwordx4 v149, s[16:17]
	s_nop 0
	s_mov_b32 m0, s23
	s_nop 0
	global_load_lds_dwordx4 v151, s[16:17]
	s_add_u32 s12, s16, 0x100000
	s_addc_u32 s13, s17, 0
	s_mov_b32 m0, s24
	s_nop 0
	global_load_lds_dwordx4 v149, s[12:13]
	s_nop 0
	s_mov_b32 m0, s25
	s_nop 0
	global_load_lds_dwordx4 v151, s[12:13]
	s_mov_b32 m0, s21
	s_nop 0
	global_load_lds_dwordx4 v148, s[18:19]
	s_nop 0
	s_mov_b32 m0, s26
	s_nop 0
	global_load_lds_dwordx4 v150, s[18:19]
	s_waitcnt vmcnt(8)
	s_waitcnt lgkmcnt(0)
	s_barrier
	s_setprio 1
	v_mfma_f32_16x16x32_bf16 v[62:65], v[154:157], v[190:193], v[62:65]
	v_mfma_f32_16x16x32_bf16 v[58:61], v[166:169], v[190:193], v[58:61]
	v_mfma_f32_16x16x32_bf16 v[46:49], v[154:157], v[198:201], v[46:49]
	v_mfma_f32_16x16x32_bf16 v[42:45], v[166:169], v[198:201], v[42:45]
	v_mfma_f32_16x16x32_bf16 v[30:33], v[154:157], v[206:209], v[30:33]
	v_mfma_f32_16x16x32_bf16 v[26:29], v[166:169], v[206:209], v[26:29]
	v_mfma_f32_16x16x32_bf16 v[14:17], v[154:157], v[214:217], v[14:17]
	v_mfma_f32_16x16x32_bf16 v[10:13], v[166:169], v[214:217], v[10:13]
	v_mfma_f32_16x16x32_bf16 v[62:65], v[158:161], v[194:197], v[62:65]
	v_mfma_f32_16x16x32_bf16 v[58:61], v[170:173], v[194:197], v[58:61]
	v_mfma_f32_16x16x32_bf16 v[46:49], v[158:161], v[202:205], v[46:49]
	v_mfma_f32_16x16x32_bf16 v[42:45], v[170:173], v[202:205], v[42:45]
	v_mfma_f32_16x16x32_bf16 v[30:33], v[158:161], v[210:213], v[30:33]
	v_mfma_f32_16x16x32_bf16 v[26:29], v[170:173], v[210:213], v[26:29]
	v_mfma_f32_16x16x32_bf16 v[14:17], v[158:161], v[218:221], v[14:17]
	v_mfma_f32_16x16x32_bf16 v[10:13], v[170:173], v[218:221], v[10:13]
	v_mfma_f32_16x16x32_bf16 v[54:57], v[174:177], v[190:193], v[54:57]
	v_mfma_f32_16x16x32_bf16 v[50:53], v[182:185], v[190:193], v[50:53]
	v_mfma_f32_16x16x32_bf16 v[38:41], v[174:177], v[198:201], v[38:41]
	v_mfma_f32_16x16x32_bf16 v[34:37], v[182:185], v[198:201], v[34:37]
	v_mfma_f32_16x16x32_bf16 v[22:25], v[174:177], v[206:209], v[22:25]
	v_mfma_f32_16x16x32_bf16 v[18:21], v[182:185], v[206:209], v[18:21]
	v_mfma_f32_16x16x32_bf16 v[6:9], v[174:177], v[214:217], v[6:9]
	v_mfma_f32_16x16x32_bf16 v[2:5], v[182:185], v[214:217], v[2:5]
	v_mfma_f32_16x16x32_bf16 v[54:57], v[178:181], v[194:197], v[54:57]
	v_mfma_f32_16x16x32_bf16 v[50:53], v[186:189], v[194:197], v[50:53]
	v_mfma_f32_16x16x32_bf16 v[38:41], v[178:181], v[202:205], v[38:41]
	v_mfma_f32_16x16x32_bf16 v[34:37], v[186:189], v[202:205], v[34:37]
	v_mfma_f32_16x16x32_bf16 v[22:25], v[178:181], v[210:213], v[22:25]
	v_mfma_f32_16x16x32_bf16 v[18:21], v[186:189], v[210:213], v[18:21]
	v_mfma_f32_16x16x32_bf16 v[6:9], v[178:181], v[218:221], v[6:9]
	v_mfma_f32_16x16x32_bf16 v[2:5], v[186:189], v[218:221], v[2:5]
	s_setprio 0
	s_barrier
; #define PG8_LDA(dst, b, h) do { _Pragma("unroll") for (int m = 0; m < 4; ++m) _Pragma("unroll") for (int k = 0; k < 2; ++k) dst[m][k] = *(const LAS bf16x8*)(lds + PG8_SA(b, h) + aoff + m * 2048 + k * 1024); } while (0)
; #define PG8_LDB(dst, b, h) do { _Pragma("unroll") for (int n = 0; n < 2; ++n) _Pragma("unroll") for (int k = 0; k < 2; ++k) dst[n][k] = *(const LAS bf16x8*)(lds + PG8_SB(b, h) + boff + n * 2048 + k * 1024); } while (0)
; #define PG8_MMA(ai, bj, At, Bt) do { __builtin_amdgcn_s_setprio(1); _Pragma("unroll") for (int m = 0; m < 4; ++m) _Pragma("unroll") for (int n = 0; n < 2; ++n) _Pragma("unroll") for (int k = 0; k < 2; ++k) \
;         acc[ai][bj][m][n] = __builtin_amdgcn_mfma_f32_16x16x32_bf16(Bt[n][k], At[m][k], acc[ai][bj][m][n], 0, 0, 0); __builtin_amdgcn_s_setprio(0); } while (0)
; #define PG8_WAIT_V(n) asm volatile("s_waitcnt vmcnt(" #n ")" ::: "memory")
; #define PG8_WAIT_L(n) asm volatile("s_waitcnt lgkmcnt(" #n ")" ::: "memory")
; #define PG8_BAR __builtin_amdgcn_s_barrier()
; #define PG8_SCHED __builtin_amdgcn_sched_barrier(0)
; template <class Epi, class Sched>
; __device__ __forceinline__ void gemm_phase(LAS unsigned char* lds, const Gemm g, const Sched& S, const Epi& E) {
;     ...
;             PG8_LDB(B0, 1, 0); PG8_LDB(B1, 1, 1); PG8_SCHED; PG8_LDA(At, 1, 0); PG8_STAGE(PG8_SA(0, 1), a2 + hstepA, voffA);
;             PG8_WAIT_V(8); PG8_WAIT_L(0); PG8_BAR; PG8_MMA(0, 0, At, B0); PG8_MMA(0, 1, At, B1); PG8_BAR; PG8_SCHED;
;             PG8_LDA(At, 1, 1); PG8_STAGE(PG8_SB(1, 0), b3, voffB); PG8_STAGE(PG8_SB(1, 1), b3 + hstepB, voffB); PG8_STAGE(PG8_SA(1, 0), a3, voffA);
;             PG8_WAIT_V(8); PG8_WAIT_L(0); PG8_BAR; PG8_MMA(1, 0, At, B0); PG8_MMA(1, 1, At, B1); PG8_BAR; PG8_SCHED;
;         }
	v_add_u32_e32 v146, 0x18000, v152
	ds_read_b128 v[154:157], v146
	ds_read_b128 v[158:161], v146 offset:1024
	ds_read_b128 v[166:169], v146 offset:2048
	ds_read_b128 v[170:173], v146 offset:3072
	v_add_u32_e32 v146, 0x1c000, v152
	ds_read_b128 v[174:177], v146
	ds_read_b128 v[178:181], v146 offset:1024
	ds_read_b128 v[182:185], v146 offset:2048
	ds_read_b128 v[186:189], v146 offset:3072
	ds_read_b128 v[190:193], v153 offset:32768
	ds_read_b128 v[194:197], v153 offset:33792
	ds_read_b128 v[198:201], v153 offset:34816
	ds_read_b128 v[202:205], v153 offset:35840
	ds_read_b128 v[206:209], v153 offset:36864
	ds_read_b128 v[210:213], v153 offset:37888
	ds_read_b128 v[214:217], v153 offset:38912
	ds_read_b128 v[218:221], v153 offset:39936
	s_add_u32 s12, s18, 0x2000
	s_addc_u32 s13, s19, 0
	s_mov_b32 m0, s28
	s_nop 0
	global_load_lds_dwordx4 v148, s[12:13]
	s_nop 0
	s_mov_b32 m0, s30
	s_nop 0
	global_load_lds_dwordx4 v150, s[12:13]
	s_waitcnt vmcnt(8)
	s_waitcnt lgkmcnt(0)
	s_barrier
	s_setprio 1
	v_mfma_f32_16x16x32_bf16 v[126:129], v[154:157], v[190:193], v[126:129]
	v_mfma_f32_16x16x32_bf16 v[122:125], v[166:169], v[190:193], v[122:125]
	v_mfma_f32_16x16x32_bf16 v[110:113], v[154:157], v[198:201], v[110:113]
	v_mfma_f32_16x16x32_bf16 v[106:109], v[166:169], v[198:201], v[106:109]
	v_mfma_f32_16x16x32_bf16 v[94:97], v[154:157], v[206:209], v[94:97]
	v_mfma_f32_16x16x32_bf16 v[90:93], v[166:169], v[206:209], v[90:93]
	v_mfma_f32_16x16x32_bf16 v[78:81], v[154:157], v[214:217], v[78:81]
	v_mfma_f32_16x16x32_bf16 v[74:77], v[166:169], v[214:217], v[74:77]
	v_mfma_f32_16x16x32_bf16 v[126:129], v[158:161], v[194:197], v[126:129]
	v_mfma_f32_16x16x32_bf16 v[122:125], v[170:173], v[194:197], v[122:125]
	v_mfma_f32_16x16x32_bf16 v[110:113], v[158:161], v[202:205], v[110:113]
	v_mfma_f32_16x16x32_bf16 v[106:109], v[170:173], v[202:205], v[106:109]
	v_mfma_f32_16x16x32_bf16 v[94:97], v[158:161], v[210:213], v[94:97]
	v_mfma_f32_16x16x32_bf16 v[90:93], v[170:173], v[210:213], v[90:93]
	v_mfma_f32_16x16x32_bf16 v[78:81], v[158:161], v[218:221], v[78:81]
	v_mfma_f32_16x16x32_bf16 v[74:77], v[170:173], v[218:221], v[74:77]
	v_mfma_f32_16x16x32_bf16 v[118:121], v[174:177], v[190:193], v[118:121]
	v_mfma_f32_16x16x32_bf16 v[114:117], v[182:185], v[190:193], v[114:117]
	v_mfma_f32_16x16x32_bf16 v[102:105], v[174:177], v[198:201], v[102:105]
	v_mfma_f32_16x16x32_bf16 v[98:101], v[182:185], v[198:201], v[98:101]
	v_mfma_f32_16x16x32_bf16 v[86:89], v[174:177], v[206:209], v[86:89]
	v_mfma_f32_16x16x32_bf16 v[82:85], v[182:185], v[206:209], v[82:85]
	v_mfma_f32_16x16x32_bf16 v[70:73], v[174:177], v[214:217], v[70:73]
	v_mfma_f32_16x16x32_bf16 v[66:69], v[182:185], v[214:217], v[66:69]
	v_mfma_f32_16x16x32_bf16 v[118:121], v[178:181], v[194:197], v[118:121]
	v_mfma_f32_16x16x32_bf16 v[114:117], v[186:189], v[194:197], v[114:117]
	v_mfma_f32_16x16x32_bf16 v[102:105], v[178:181], v[202:205], v[102:105]
	v_mfma_f32_16x16x32_bf16 v[98:101], v[186:189], v[202:205], v[98:101]
	v_mfma_f32_16x16x32_bf16 v[86:89], v[178:181], v[210:213], v[86:89]
	v_mfma_f32_16x16x32_bf16 v[82:85], v[186:189], v[210:213], v[82:85]
	v_mfma_f32_16x16x32_bf16 v[70:73], v[178:181], v[218:221], v[70:73]
	v_mfma_f32_16x16x32_bf16 v[66:69], v[186:189], v[218:221], v[66:69]
	s_setprio 0
	s_barrier
	ds_read_b128 v[190:193], v153 offset:49152
	ds_read_b128 v[194:197], v153 offset:50176
	ds_read_b128 v[198:201], v153 offset:51200
	ds_read_b128 v[202:205], v153 offset:52224
	ds_read_b128 v[206:209], v153 offset:53248
	ds_read_b128 v[210:213], v153 offset:54272
	ds_read_b128 v[214:217], v153 offset:55296
	ds_read_b128 v[218:221], v153 offset:56320
	s_add_u32 s12, s16, 0x80
	s_addc_u32 s13, s17, 0
	s_mov_b32 m0, s31
	s_nop 0
	global_load_lds_dwordx4 v149, s[12:13]
	s_nop 0
	s_mov_b32 m0, s35
	s_nop 0
	global_load_lds_dwordx4 v151, s[12:13]
	s_add_u32 s12, s16, 0x100080
	s_addc_u32 s13, s17, 0
	s_mov_b32 m0, s48
	s_nop 0
	global_load_lds_dwordx4 v149, s[12:13]
	s_nop 0
	s_mov_b32 m0, s49
	s_nop 0
	global_load_lds_dwordx4 v151, s[12:13]
	s_mov_b32 m0, s38
	s_nop 0
	global_load_lds_dwordx4 v148, s[14:15]
	s_nop 0
	s_mov_b32 m0, s39
	s_nop 0
	global_load_lds_dwordx4 v150, s[14:15]
	s_waitcnt vmcnt(8)
	s_waitcnt lgkmcnt(0)
	s_barrier
	s_setprio 1
	v_mfma_f32_16x16x32_bf16 v[62:65], v[154:157], v[190:193], v[62:65]
	v_mfma_f32_16x16x32_bf16 v[58:61], v[166:169], v[190:193], v[58:61]
	v_mfma_f32_16x16x32_bf16 v[46:49], v[154:157], v[198:201], v[46:49]
	v_mfma_f32_16x16x32_bf16 v[42:45], v[166:169], v[198:201], v[42:45]
	v_mfma_f32_16x16x32_bf16 v[30:33], v[154:157], v[206:209], v[30:33]
	v_mfma_f32_16x16x32_bf16 v[26:29], v[166:169], v[206:209], v[26:29]
	v_mfma_f32_16x16x32_bf16 v[14:17], v[154:157], v[214:217], v[14:17]
	v_mfma_f32_16x16x32_bf16 v[10:13], v[166:169], v[214:217], v[10:13]
	v_mfma_f32_16x16x32_bf16 v[62:65], v[158:161], v[194:197], v[62:65]
	v_mfma_f32_16x16x32_bf16 v[58:61], v[170:173], v[194:197], v[58:61]
	v_mfma_f32_16x16x32_bf16 v[46:49], v[158:161], v[202:205], v[46:49]
	v_mfma_f32_16x16x32_bf16 v[42:45], v[170:173], v[202:205], v[42:45]
	v_mfma_f32_16x16x32_bf16 v[30:33], v[158:161], v[210:213], v[30:33]
	v_mfma_f32_16x16x32_bf16 v[26:29], v[170:173], v[210:213], v[26:29]
	v_mfma_f32_16x16x32_bf16 v[14:17], v[158:161], v[218:221], v[14:17]
	v_mfma_f32_16x16x32_bf16 v[10:13], v[170:173], v[218:221], v[10:13]
	v_mfma_f32_16x16x32_bf16 v[54:57], v[174:177], v[190:193], v[54:57]
	v_mfma_f32_16x16x32_bf16 v[50:53], v[182:185], v[190:193], v[50:53]
	v_mfma_f32_16x16x32_bf16 v[38:41], v[174:177], v[198:201], v[38:41]
	v_mfma_f32_16x16x32_bf16 v[34:37], v[182:185], v[198:201], v[34:37]
	v_mfma_f32_16x16x32_bf16 v[22:25], v[174:177], v[206:209], v[22:25]
	v_mfma_f32_16x16x32_bf16 v[18:21], v[182:185], v[206:209], v[18:21]
	v_mfma_f32_16x16x32_bf16 v[6:9], v[174:177], v[214:217], v[6:9]
	v_mfma_f32_16x16x32_bf16 v[2:5], v[182:185], v[214:217], v[2:5]
	v_mfma_f32_16x16x32_bf16 v[54:57], v[178:181], v[194:197], v[54:57]
	v_mfma_f32_16x16x32_bf16 v[50:53], v[186:189], v[194:197], v[50:53]
	v_mfma_f32_16x16x32_bf16 v[38:41], v[178:181], v[202:205], v[38:41]
	v_mfma_f32_16x16x32_bf16 v[34:37], v[186:189], v[202:205], v[34:37]
	v_mfma_f32_16x16x32_bf16 v[22:25], v[178:181], v[210:213], v[22:25]
	v_mfma_f32_16x16x32_bf16 v[18:21], v[186:189], v[210:213], v[18:21]
	v_mfma_f32_16x16x32_bf16 v[6:9], v[178:181], v[218:221], v[6:9]
	v_mfma_f32_16x16x32_bf16 v[2:5], v[186:189], v[218:221], v[2:5]
	s_setprio 0
	s_barrier
	s_add_i32 s73, s73, 2
	s_add_u32 s45, s45, 0x100
	s_addc_u32 s72, s72, 0
	s_cmp_gt_u32 s73, 61
	s_mov_b64 s[12:13], s[98:99]
	s_cbranch_scc0 .LBB0_780
	s_and_b64 vcc, exec, s[6:7]
	s_cbranch_vccz .LBB0_783
	s_barrier
